# nt cache policy on once-read streams: P1 x loads, P5 epilogue x loads, P8 epilogue x1 loads, final-norm output stores
# speedup vs baseline: 1.0136x; 1.0136x over previous
.LBB0_203:
	v_add_co_u32_e32 v32, vcc, 0xffffd000, v104
	global_load_dwordx4 v[20:23], v[104:105], off offset:-3072 nt
	s_nop 0
	v_addc_co_u32_e32 v33, vcc, -1, v105, vcc
	v_add_co_u32_e32 v34, vcc, 0xffffe000, v104
	global_load_dwordx4 v[28:31], v[104:105], off offset:-2048 nt
	global_load_dwordx4 v[24:27], v[104:105], off offset:-1024 nt
	global_load_dwordx4 v[16:19], v[104:105], off nt
	global_load_dwordx4 v[76:79], v[32:33], off offset:-3072 nt
	global_load_dwordx4 v[68:71], v[32:33], off offset:-2048 nt
	global_load_dwordx4 v[64:67], v[32:33], off nt
	global_load_dwordx4 v[72:75], v[32:33], off offset:-1024 nt
	v_addc_co_u32_e32 v35, vcc, -1, v105, vcc
	global_load_dwordx4 v[60:63], v[34:35], off offset:-3072 nt
	global_load_dwordx4 v[52:55], v[34:35], off offset:-2048 nt
	global_load_dwordx4 v[48:51], v[34:35], off nt
	global_load_dwordx4 v[56:59], v[34:35], off offset:-1024 nt
	v_add_co_u32_e32 v40, vcc, 0xfffff000, v104
	v_add_co_u32_e64 v106, s[0:1], s9, v86
	s_nop 0
	v_addc_co_u32_e32 v41, vcc, -1, v105, vcc
	global_load_dwordx4 v[44:47], v[40:41], off offset:-3072 nt
	global_load_dwordx4 v[36:39], v[40:41], off offset:-2048 nt
	global_load_dwordx4 v[32:35], v[104:105], off offset:-4096 nt
	s_nop 0
	global_load_dwordx4 v[40:43], v[40:41], off offset:-1024 nt
	v_addc_co_u32_e64 v107, s[0:1], -1, v87, s[0:1]
	s_add_i32 s20, s20, 4
	s_cmp_lt_u32 s20, 28
	v_lshl_add_u64 v[104:105], v[104:105], 0, s[16:17]
	s_waitcnt vmcnt(15)
	v_pk_mul_f32 v[120:121], v[22:23], v[22:23]
	v_pk_mul_f32 v[122:123], v[20:21], v[20:21]
	s_waitcnt vmcnt(14)
	v_pk_mul_f32 v[124:125], v[30:31], v[30:31]
	v_pk_mul_f32 v[126:127], v[28:29], v[28:29]
	s_waitcnt vmcnt(13)
	v_mul_f32_e32 v128, v25, v25
	v_mul_f32_e32 v130, v27, v27
	v_pk_mov_b32 v[132:133], v[122:123], v[120:121] op_sel:[1,0]
	v_mov_b32_e32 v123, v121
	v_pk_mov_b32 v[120:121], v[126:127], v[124:125] op_sel:[1,0]
	v_mov_b32_e32 v127, v125
	s_waitcnt vmcnt(12)
	v_mul_f32_e32 v141, v18, v18
	v_mul_f32_e32 v143, v19, v19
	v_pk_fma_f32 v[124:125], v[24:25], v[24:25], v[128:129] op_sel_hi:[1,1,0]
	v_pk_fma_f32 v[128:129], v[26:27], v[26:27], v[130:131] op_sel_hi:[1,1,0]
	s_waitcnt vmcnt(11)
	v_pk_mul_f32 v[130:131], v[78:79], v[78:79]
	v_pk_mul_f32 v[134:135], v[76:77], v[76:77]
	s_waitcnt vmcnt(10)
	v_pk_mul_f32 v[136:137], v[70:71], v[70:71]
	v_pk_mul_f32 v[138:139], v[68:69], v[68:69]
	s_waitcnt vmcnt(8)
	v_mul_f32_e32 v140, v73, v73
	v_mul_f32_e32 v142, v75, v75
	v_pk_add_f32 v[122:123], v[132:133], v[122:123]
	v_pk_add_f32 v[120:121], v[120:121], v[126:127]
	v_mul_f32_e32 v155, v16, v16
	v_mul_f32_e32 v157, v17, v17
	v_mul_f32_e32 v149, v66, v66
	v_mul_f32_e32 v151, v67, v67
	v_mov_b32_e32 v125, v141
	v_mov_b32_e32 v129, v143
	v_pk_mov_b32 v[126:127], v[134:135], v[130:131] op_sel:[1,0]
	v_mov_b32_e32 v135, v131
	v_pk_mov_b32 v[130:131], v[138:139], v[136:137] op_sel:[1,0]
	v_mov_b32_e32 v139, v137
	v_pk_fma_f32 v[132:133], v[72:73], v[72:73], v[140:141] op_sel_hi:[1,1,0]
	v_pk_fma_f32 v[136:137], v[74:75], v[74:75], v[142:143] op_sel_hi:[1,1,0]
	s_waitcnt vmcnt(7)
	v_pk_mul_f32 v[140:141], v[62:63], v[62:63]
	v_pk_mul_f32 v[142:143], v[60:61], v[60:61]
	s_waitcnt vmcnt(6)
	v_pk_mul_f32 v[144:145], v[54:55], v[54:55]
	v_pk_mul_f32 v[146:147], v[52:53], v[52:53]
	s_waitcnt vmcnt(4)
	v_mul_f32_e32 v148, v57, v57
	v_mul_f32_e32 v150, v59, v59
	v_pk_add_f32 v[122:123], v[122:123], v[122:123] op_sel:[0,1] op_sel_hi:[1,0]
	v_pk_add_f32 v[120:121], v[120:121], v[120:121] op_sel:[0,1] op_sel_hi:[1,0]
	v_mul_f32_e32 v162, v50, v50
	v_mul_f32_e32 v163, v51, v51
	v_pk_add_f32 v[124:125], v[124:125], v[128:129]
	v_pk_add_f32 v[126:127], v[126:127], v[134:135]
	v_pk_add_f32 v[128:129], v[130:131], v[138:139]
	v_mov_b32_e32 v133, v149
	v_mov_b32_e32 v137, v151
	v_pk_mov_b32 v[130:131], v[142:143], v[140:141] op_sel:[1,0]
	v_mov_b32_e32 v143, v141
	v_pk_mov_b32 v[134:135], v[146:147], v[144:145] op_sel:[1,0]
	v_mov_b32_e32 v147, v145
	v_pk_fma_f32 v[138:139], v[56:57], v[56:57], v[148:149] op_sel_hi:[1,1,0]
	v_pk_fma_f32 v[140:141], v[58:59], v[58:59], v[150:151] op_sel_hi:[1,1,0]
	s_waitcnt vmcnt(3)
	v_pk_mul_f32 v[144:145], v[46:47], v[46:47]
	v_pk_mul_f32 v[148:149], v[44:45], v[44:45]
	s_waitcnt vmcnt(2)
	v_pk_mul_f32 v[150:151], v[38:39], v[38:39]
	v_pk_mul_f32 v[152:153], v[36:37], v[36:37]
	v_mov_b32_e32 v123, v155
	v_mov_b32_e32 v121, v157
	v_mul_f32_e32 v158, v64, v64
	v_mul_f32_e32 v159, v65, v65
	v_pk_add_f32 v[126:127], v[126:127], v[126:127] op_sel:[0,1] op_sel_hi:[1,0]
	v_pk_add_f32 v[128:129], v[128:129], v[128:129] op_sel:[0,1] op_sel_hi:[1,0]
	v_pk_add_f32 v[132:133], v[132:133], v[136:137]
	v_pk_add_f32 v[130:131], v[130:131], v[142:143]
	v_pk_add_f32 v[134:135], v[134:135], v[146:147]
	v_mov_b32_e32 v139, v162
	v_mov_b32_e32 v141, v163
	v_pk_mov_b32 v[136:137], v[148:149], v[144:145] op_sel:[1,0]
	v_mov_b32_e32 v149, v145
	v_pk_mov_b32 v[142:143], v[152:153], v[150:151] op_sel:[1,0]
	v_mov_b32_e32 v153, v151
	v_pk_add_f32 v[120:121], v[122:123], v[120:121]
	v_mul_f32_e32 v160, v48, v48
	v_mul_f32_e32 v161, v49, v49
	s_waitcnt vmcnt(0)
	v_mul_f32_e32 v154, v41, v41
	v_mul_f32_e32 v156, v43, v43
	v_mov_b32_e32 v127, v158
	v_mov_b32_e32 v129, v159
	v_pk_add_f32 v[122:123], v[130:131], v[130:131] op_sel:[0,1] op_sel_hi:[1,0]
	v_pk_add_f32 v[130:131], v[134:135], v[134:135] op_sel:[0,1] op_sel_hi:[1,0]
	v_pk_add_f32 v[134:135], v[138:139], v[140:141]
	v_pk_add_f32 v[136:137], v[136:137], v[148:149]
	v_pk_add_f32 v[138:139], v[142:143], v[152:153]
	v_pk_add_f32 v[120:121], v[120:121], v[124:125]
	v_mul_f32_e32 v164, v32, v32
	v_mul_f32_e32 v165, v33, v33
	v_mul_f32_e32 v166, v34, v34
	v_mul_f32_e32 v167, v35, v35
	v_pk_fma_f32 v[144:145], v[40:41], v[40:41], v[154:155] op_sel_hi:[1,1,0]
	v_pk_fma_f32 v[146:147], v[42:43], v[42:43], v[156:157] op_sel_hi:[1,1,0]
	v_pk_add_f32 v[124:125], v[126:127], v[128:129]
	v_mov_b32_e32 v123, v160
	v_mov_b32_e32 v131, v161
	v_pk_add_f32 v[126:127], v[136:137], v[136:137] op_sel:[0,1] op_sel_hi:[1,0]
	v_pk_add_f32 v[128:129], v[138:139], v[138:139] op_sel:[0,1] op_sel_hi:[1,0]
	v_add_f32_e32 v138, v120, v121
	v_mov_b32_e32 v145, v166
	v_mov_b32_e32 v147, v167
	v_pk_add_f32 v[120:121], v[124:125], v[132:133]
	v_pk_add_f32 v[122:123], v[122:123], v[130:131]
	v_mov_b32_e32 v127, v164
	v_mov_b32_e32 v129, v165
	ds_bpermute_b32 v124, v108, v138
	v_pk_add_f32 v[136:137], v[144:145], v[146:147]
	v_add_f32_e32 v125, v120, v121
	v_pk_add_f32 v[120:121], v[122:123], v[134:135]
	v_pk_add_f32 v[122:123], v[126:127], v[128:129]
	v_add_f32_e32 v126, v120, v121
	v_pk_add_f32 v[120:121], v[122:123], v[136:137]
	ds_bpermute_b32 v122, v108, v125
	v_add_f32_e32 v120, v120, v121
	ds_bpermute_b32 v121, v108, v126
	ds_bpermute_b32 v123, v108, v120
	s_waitcnt lgkmcnt(0)
	v_add_f32_e32 v124, v138, v124
	ds_bpermute_b32 v127, v109, v124
	v_add_f32_e32 v122, v125, v122
	v_add_f32_e32 v121, v126, v121
	ds_bpermute_b32 v125, v109, v122
	v_add_f32_e32 v120, v120, v123
	ds_bpermute_b32 v123, v109, v121
	s_waitcnt lgkmcnt(2)
	v_add_f32_e32 v124, v124, v127
	ds_bpermute_b32 v126, v109, v120
	ds_bpermute_b32 v127, v110, v124
	s_waitcnt lgkmcnt(3)
	v_add_f32_e32 v122, v122, v125
	s_waitcnt lgkmcnt(2)
	v_add_f32_e32 v121, v121, v123
	ds_bpermute_b32 v123, v110, v122
	ds_bpermute_b32 v125, v110, v121
	s_waitcnt lgkmcnt(3)
	v_add_f32_e32 v120, v120, v126
	s_waitcnt lgkmcnt(2)
	v_add_f32_e32 v124, v124, v127
	ds_bpermute_b32 v126, v110, v120
	ds_bpermute_b32 v127, v111, v124
	s_waitcnt lgkmcnt(3)
	v_add_f32_e32 v122, v122, v123
	ds_bpermute_b32 v123, v111, v122
	s_waitcnt lgkmcnt(3)
	v_add_f32_e32 v121, v121, v125
	ds_bpermute_b32 v125, v111, v121
	s_waitcnt lgkmcnt(3)
	v_add_f32_e32 v120, v120, v126
	s_waitcnt lgkmcnt(2)
	v_add_f32_e32 v124, v124, v127
	ds_bpermute_b32 v126, v111, v120
	ds_bpermute_b32 v127, v112, v124
	s_waitcnt lgkmcnt(3)
	v_add_f32_e32 v122, v122, v123
	ds_bpermute_b32 v123, v112, v122
	s_waitcnt lgkmcnt(3)
	v_add_f32_e32 v121, v121, v125
	ds_bpermute_b32 v125, v112, v121
	s_waitcnt lgkmcnt(3)
	v_add_f32_e32 v120, v120, v126
	s_waitcnt lgkmcnt(2)
	v_add_f32_e32 v124, v124, v127
	ds_bpermute_b32 v126, v112, v120
	ds_bpermute_b32 v127, v113, v124
	s_waitcnt lgkmcnt(3)
	v_add_f32_e32 v122, v122, v123
	ds_bpermute_b32 v123, v113, v122
	s_waitcnt lgkmcnt(3)
	v_add_f32_e32 v121, v121, v125
	ds_bpermute_b32 v125, v113, v121
	s_waitcnt lgkmcnt(3)
	v_add_f32_e32 v120, v120, v126
	s_waitcnt lgkmcnt(2)
	v_add_f32_e32 v124, v124, v127
	ds_bpermute_b32 v126, v113, v120
	v_fmamk_f32 v124, v124, 0x3a800000, v118
	s_waitcnt lgkmcnt(2)
	v_add_f32_e32 v122, v122, v123
	v_mul_f32_e32 v123, 0x4f800000, v124
	v_cmp_gt_f32_e32 vcc, s11, v124
	v_fmamk_f32 v122, v122, 0x3a800000, v118
	s_waitcnt lgkmcnt(1)
	v_add_f32_e32 v121, v121, v125
	v_cndmask_b32_e32 v123, v124, v123, vcc
	v_mul_f32_e32 v124, 0x4f800000, v122
	v_sqrt_f32_e32 v125, v123
	v_cmp_gt_f32_e64 s[0:1], s11, v122
	v_fmamk_f32 v121, v121, 0x3a800000, v118
	s_waitcnt lgkmcnt(0)
	v_add_f32_e32 v120, v120, v126
	v_cndmask_b32_e64 v122, v122, v124, s[0:1]
	v_mul_f32_e32 v124, 0x4f800000, v121
	v_cmp_gt_f32_e64 s[2:3], s11, v121
	v_sqrt_f32_e32 v126, v122
	v_fmamk_f32 v120, v120, 0x3a800000, v118
	v_cndmask_b32_e64 v121, v121, v124, s[2:3]
	v_mul_f32_e32 v124, 0x4f800000, v120
	v_cmp_gt_f32_e64 s[4:5], s11, v120
	v_sqrt_f32_e32 v127, v121
	v_add_u32_e32 v128, -1, v125
	v_cndmask_b32_e64 v120, v120, v124, s[4:5]
	v_add_u32_e32 v129, 1, v125
	v_fma_f32 v130, -v128, v125, v123
	v_sqrt_f32_e32 v124, v120
	v_fma_f32 v131, -v129, v125, v123
	v_add_u32_e32 v132, -1, v126
	v_cmp_ge_f32_e64 s[6:7], 0, v130
	v_add_u32_e32 v133, 1, v126
	v_fma_f32 v130, -v133, v126, v122
	v_cndmask_b32_e64 v125, v125, v128, s[6:7]
	v_cmp_lt_f32_e64 s[6:7], 0, v131
	v_fma_f32 v128, -v132, v126, v122
	v_add_u32_e32 v131, -1, v127
	v_cndmask_b32_e64 v125, v125, v129, s[6:7]
	v_cmp_ge_f32_e64 s[6:7], 0, v128
	v_add_u32_e32 v134, 1, v127
	v_fma_f32 v128, -v131, v127, v121
	v_cndmask_b32_e64 v126, v126, v132, s[6:7]
	v_cmp_lt_f32_e64 s[6:7], 0, v130
	v_fma_f32 v129, -v134, v127, v121
	v_add_u32_e32 v132, -1, v124
	v_cndmask_b32_e64 v126, v126, v133, s[6:7]
	v_cmp_ge_f32_e64 s[6:7], 0, v128
	v_add_u32_e32 v135, 1, v124
	v_fma_f32 v128, -v132, v124, v120
	v_cndmask_b32_e64 v127, v127, v131, s[6:7]
	v_cmp_lt_f32_e64 s[6:7], 0, v129
	v_mul_f32_e32 v136, 0x37800000, v125
	v_fma_f32 v129, -v135, v124, v120
	v_cndmask_b32_e64 v127, v127, v134, s[6:7]
	v_cmp_ge_f32_e64 s[6:7], 0, v128
	v_cndmask_b32_e32 v125, v125, v136, vcc
	v_cmp_class_f32_e32 vcc, v123, v119
	v_mul_f32_e32 v130, 0x37800000, v126
	v_cndmask_b32_e64 v124, v124, v132, s[6:7]
	v_cmp_lt_f32_e64 s[6:7], 0, v129
	v_cndmask_b32_e32 v123, v125, v123, vcc
	v_cndmask_b32_e64 v125, v126, v130, s[0:1]
	v_mul_f32_e32 v126, 0x37800000, v127
	v_cndmask_b32_e64 v124, v124, v135, s[6:7]
	v_cmp_class_f32_e32 vcc, v122, v119
	v_div_scale_f32 v128, s[0:1], v123, v123, 1.0
	s_nop 0
	v_cndmask_b32_e32 v122, v125, v122, vcc
	v_cndmask_b32_e64 v125, v127, v126, s[2:3]
	v_cmp_class_f32_e32 vcc, v121, v119
	v_mul_f32_e32 v126, 0x37800000, v124
	v_rcp_f32_e32 v127, v128
	v_div_scale_f32 v130, s[2:3], v122, v122, 1.0
	v_cndmask_b32_e32 v121, v125, v121, vcc
	v_cndmask_b32_e64 v124, v124, v126, s[4:5]
	v_cmp_class_f32_e32 vcc, v120, v119
	v_rcp_f32_e32 v125, v130
	v_div_scale_f32 v126, s[4:5], v121, v121, 1.0
	v_cndmask_b32_e32 v124, v124, v120, vcc
	v_rcp_f32_e32 v133, v126
	v_div_scale_f32 v134, s[6:7], v124, v124, 1.0
	v_rcp_f32_e32 v136, v134
	v_fma_f32 v120, -v128, v127, 1.0
	v_div_scale_f32 v129, s[0:1], 1.0, v123, 1.0
	v_fmac_f32_e32 v127, v120, v127
	v_fma_f32 v120, -v130, v125, 1.0
	v_div_scale_f32 v131, s[2:3], 1.0, v122, 1.0
	v_mul_f32_e32 v137, v129, v127
	v_fmac_f32_e32 v125, v120, v125
	v_fma_f32 v120, -v126, v133, 1.0
	v_div_scale_f32 v132, s[4:5], 1.0, v121, 1.0
	v_fma_f32 v138, -v128, v137, v129
	v_mul_f32_e32 v139, v131, v125
	v_fmac_f32_e32 v133, v120, v133
	v_fma_f32 v120, -v134, v136, 1.0
	v_div_scale_f32 v135, s[6:7], 1.0, v124, 1.0
	v_fmac_f32_e32 v137, v138, v127
	v_fma_f32 v138, -v130, v139, v131
	v_mul_f32_e32 v140, v132, v133
	v_fmac_f32_e32 v136, v120, v136
	v_fma_f32 v128, -v128, v137, v129
	v_fmac_f32_e32 v139, v138, v125
	v_fma_f32 v120, -v126, v140, v132
	v_mul_f32_e32 v129, v135, v136
	v_fma_f32 v130, -v130, v139, v131
	v_fmac_f32_e32 v140, v120, v133
	v_fma_f32 v120, -v134, v129, v135
	s_mov_b64 vcc, s[2:3]
	v_div_fmas_f32 v125, v130, v125, v139
	v_fma_f32 v126, -v126, v140, v132
	v_fmac_f32_e32 v129, v120, v136
	s_mov_b64 vcc, s[4:5]
	v_div_fixup_f32 v120, v125, v122, 1.0
	v_div_fmas_f32 v122, v126, v133, v140
	v_fma_f32 v125, -v134, v129, v135
	s_mov_b64 vcc, s[6:7]
	v_pk_mul_f32 v[76:77], v[76:77], v[120:121] op_sel_hi:[1,0]
	v_pk_mul_f32 v[78:79], v[78:79], v[120:121] op_sel_hi:[1,0]
	v_pk_mul_f32 v[68:69], v[68:69], v[120:121] op_sel_hi:[1,0]
	v_pk_mul_f32 v[70:71], v[70:71], v[120:121] op_sel_hi:[1,0]
	v_pk_mul_f32 v[72:73], v[72:73], v[120:121] op_sel_hi:[1,0]
	v_pk_mul_f32 v[74:75], v[74:75], v[120:121] op_sel_hi:[1,0]
	v_pk_mul_f32 v[64:65], v[64:65], v[120:121] op_sel_hi:[1,0]
	v_pk_mul_f32 v[66:67], v[66:67], v[120:121] op_sel_hi:[1,0]
	v_div_fixup_f32 v120, v122, v121, 1.0
	v_div_fmas_f32 v121, v125, v136, v129
	s_mov_b64 vcc, s[0:1]
	v_pk_fma_f32 v[78:79], v[88:89], v[78:79], v[2:3]
	v_pk_fma_f32 v[76:77], v[90:91], v[76:77], v[0:1]
	v_pk_fma_f32 v[68:69], v[94:95], v[68:69], v[4:5]
	v_pk_mul_f32 v[60:61], v[60:61], v[120:121] op_sel_hi:[1,0]
	v_pk_mul_f32 v[62:63], v[62:63], v[120:121] op_sel_hi:[1,0]
	v_pk_mul_f32 v[52:53], v[52:53], v[120:121] op_sel_hi:[1,0]
	v_pk_mul_f32 v[54:55], v[54:55], v[120:121] op_sel_hi:[1,0]
	v_pk_mul_f32 v[56:57], v[56:57], v[120:121] op_sel_hi:[1,0]
	v_pk_mul_f32 v[58:59], v[58:59], v[120:121] op_sel_hi:[1,0]
	v_pk_mul_f32 v[48:49], v[48:49], v[120:121] op_sel_hi:[1,0]
	v_pk_mul_f32 v[50:51], v[50:51], v[120:121] op_sel_hi:[1,0]
	v_div_fixup_f32 v120, v121, v124, 1.0
	v_div_fmas_f32 v121, v128, v127, v137
	v_pk_fma_f32 v[70:71], v[92:93], v[70:71], v[6:7]
	v_pk_fma_f32 v[64:65], v[102:103], v[64:65], v[12:13]
	v_cvt_pk_bf16_f32 v76, v76, v77
	v_cvt_pk_bf16_f32 v77, v78, v79
	v_pk_fma_f32 v[60:61], v[90:91], v[60:61], v[0:1]
	v_pk_fma_f32 v[52:53], v[94:95], v[52:53], v[4:5]
	v_pk_mul_f32 v[44:45], v[44:45], v[120:121] op_sel_hi:[1,0]
	v_pk_mul_f32 v[36:37], v[36:37], v[120:121] op_sel_hi:[1,0]
	v_div_fixup_f32 v78, v121, v123, 1.0
	global_store_dwordx2 v[106:107], v[76:77], off offset:-3584
	v_cvt_pk_bf16_f32 v68, v68, v69
	v_cvt_pk_bf16_f32 v69, v70, v71
	v_pk_fma_f32 v[74:75], v[96:97], v[74:75], v[10:11]
	v_pk_fma_f32 v[72:73], v[98:99], v[72:73], v[8:9]
	v_pk_fma_f32 v[66:67], v[100:101], v[66:67], v[14:15]
	v_pk_fma_f32 v[62:63], v[88:89], v[62:63], v[2:3]
	v_pk_fma_f32 v[54:55], v[92:93], v[54:55], v[6:7]
	v_pk_fma_f32 v[48:49], v[102:103], v[48:49], v[12:13]
	v_pk_mul_f32 v[46:47], v[46:47], v[120:121] op_sel_hi:[1,0]
	v_pk_mul_f32 v[38:39], v[38:39], v[120:121] op_sel_hi:[1,0]
	v_pk_mul_f32 v[32:33], v[32:33], v[120:121] op_sel_hi:[1,0]
	v_pk_fma_f32 v[44:45], v[90:91], v[44:45], v[0:1]
	v_pk_fma_f32 v[36:37], v[94:95], v[36:37], v[4:5]
	v_pk_mul_f32 v[20:21], v[20:21], v[78:79] op_sel_hi:[1,0]
	global_store_dwordx2 v[106:107], v[68:69], off offset:-3072
	v_cvt_pk_bf16_f32 v68, v72, v73
	v_cvt_pk_bf16_f32 v69, v74, v75
	global_store_dwordx2 v[106:107], v[68:69], off offset:-2560
	v_cvt_pk_bf16_f32 v64, v64, v65
	v_cvt_pk_bf16_f32 v65, v66, v67
	global_store_dwordx2 v[106:107], v[64:65], off offset:-2048
	v_cvt_pk_bf16_f32 v60, v60, v61
	v_cvt_pk_bf16_f32 v61, v62, v63
	global_store_dwordx2 v[106:107], v[60:61], off offset:-1536
	v_cvt_pk_bf16_f32 v52, v52, v53
	v_cvt_pk_bf16_f32 v53, v54, v55
	v_pk_fma_f32 v[58:59], v[96:97], v[58:59], v[10:11]
	v_pk_fma_f32 v[56:57], v[98:99], v[56:57], v[8:9]
	v_pk_fma_f32 v[50:51], v[100:101], v[50:51], v[14:15]
	v_pk_mul_f32 v[40:41], v[40:41], v[120:121] op_sel_hi:[1,0]
	v_pk_mul_f32 v[42:43], v[42:43], v[120:121] op_sel_hi:[1,0]
	v_pk_mul_f32 v[34:35], v[34:35], v[120:121] op_sel_hi:[1,0]
	v_pk_fma_f32 v[46:47], v[88:89], v[46:47], v[2:3]
	v_pk_fma_f32 v[38:39], v[92:93], v[38:39], v[6:7]
	v_pk_fma_f32 v[32:33], v[102:103], v[32:33], v[12:13]
	v_pk_mul_f32 v[22:23], v[22:23], v[78:79] op_sel_hi:[1,0]
	v_pk_fma_f32 v[20:21], v[90:91], v[20:21], v[0:1]
	global_store_dwordx2 v[106:107], v[52:53], off offset:-1024
	v_cvt_pk_bf16_f32 v52, v56, v57
	v_cvt_pk_bf16_f32 v53, v58, v59
	global_store_dwordx2 v[106:107], v[52:53], off offset:-512
	v_cvt_pk_bf16_f32 v48, v48, v49
	v_cvt_pk_bf16_f32 v49, v50, v51
	global_store_dwordx2 v[86:87], v[48:49], off offset:-4096
	v_cvt_pk_bf16_f32 v44, v44, v45
	v_cvt_pk_bf16_f32 v45, v46, v47
	global_store_dwordx2 v[86:87], v[44:45], off offset:-3584
	v_cvt_pk_bf16_f32 v36, v36, v37
	v_cvt_pk_bf16_f32 v37, v38, v39
	v_pk_fma_f32 v[42:43], v[96:97], v[42:43], v[10:11]
	v_pk_fma_f32 v[40:41], v[98:99], v[40:41], v[8:9]
	v_pk_fma_f32 v[34:35], v[100:101], v[34:35], v[14:15]
	v_pk_mul_f32 v[28:29], v[28:29], v[78:79] op_sel_hi:[1,0]
	v_pk_mul_f32 v[30:31], v[30:31], v[78:79] op_sel_hi:[1,0]
	v_pk_mul_f32 v[16:17], v[16:17], v[78:79] op_sel_hi:[1,0]
	v_pk_fma_f32 v[22:23], v[88:89], v[22:23], v[2:3]
	global_store_dwordx2 v[86:87], v[36:37], off offset:-3072
	v_cvt_pk_bf16_f32 v36, v40, v41
	v_cvt_pk_bf16_f32 v37, v42, v43
	global_store_dwordx2 v[86:87], v[36:37], off offset:-2560
	v_cvt_pk_bf16_f32 v32, v32, v33
	v_cvt_pk_bf16_f32 v33, v34, v35
	global_store_dwordx2 v[86:87], v[32:33], off offset:-2048
	v_cvt_pk_bf16_f32 v20, v20, v21
	v_cvt_pk_bf16_f32 v21, v22, v23
	v_pk_mul_f32 v[24:25], v[24:25], v[78:79] op_sel_hi:[1,0]
	v_pk_mul_f32 v[26:27], v[26:27], v[78:79] op_sel_hi:[1,0]
	v_pk_mul_f32 v[18:19], v[18:19], v[78:79] op_sel_hi:[1,0]
	v_pk_fma_f32 v[30:31], v[92:93], v[30:31], v[6:7]
	v_pk_fma_f32 v[28:29], v[94:95], v[28:29], v[4:5]
	v_pk_fma_f32 v[16:17], v[102:103], v[16:17], v[12:13]
	global_store_dwordx2 v[86:87], v[20:21], off offset:-1536
	v_cvt_pk_bf16_f32 v20, v28, v29
	v_cvt_pk_bf16_f32 v21, v30, v31
	v_pk_fma_f32 v[26:27], v[96:97], v[26:27], v[10:11]
	v_pk_fma_f32 v[24:25], v[98:99], v[24:25], v[8:9]
	v_pk_fma_f32 v[18:19], v[100:101], v[18:19], v[14:15]
	global_store_dwordx2 v[86:87], v[20:21], off offset:-1024
	v_cvt_pk_bf16_f32 v20, v24, v25
	v_cvt_pk_bf16_f32 v21, v26, v27
	global_store_dwordx2 v[86:87], v[20:21], off offset:-512
	v_cvt_pk_bf16_f32 v16, v16, v17
	v_cvt_pk_bf16_f32 v17, v18, v19
	global_store_dwordx2 v[86:87], v[16:17], off
	v_lshl_add_u64 v[86:87], v[86:87], 0, s[18:19]
	s_cbranch_scc1 .LBB0_203
	s_add_i32 s8, s8, s10
	v_lshl_add_u64 v[82:83], v[82:83], 0, s[12:13]
	s_cmp_gt_i32 s8, 0xffff
	v_lshl_add_u64 v[84:85], v[84:85], 0, s[14:15]
	s_cbranch_scc0 .LBB0_202

.LBB0_757:
	s_lshl_b32 s16, s14, 8
	v_add_u32_e32 v194, s16, v149
	s_ashr_i32 s0, s14, 3
	v_lshl_or_b32 v166, s6, 8, v179
	v_ashrrev_i32_e32 v195, 31, v194
	v_readlane_b32 s60, v249, 9
	s_mul_hi_i32 s1, s0, 0x6000
	s_mulk_i32 s0, 0x6000
	v_lshlrev_b64 v[164:165], 10, v[194:195]
	v_ashrrev_i32_e32 v167, 31, v166
	v_readlane_b32 s61, v249, 10
	s_add_u32 s0, s47, s0
	v_lshl_add_u64 v[174:175], v[164:165], 0, v[166:167]
	s_mov_b64 s[4:5], s[60:61]
	s_addc_u32 s1, s48, s1
	v_lshl_add_u64 v[172:173], v[174:175], 2, s[4:5]
	v_lshl_add_u64 v[170:171], v[166:167], 2, s[0:1]
	global_load_dwordx4 v[186:189], v[172:173], off nt
	global_load_dwordx4 v[132:135], v[170:171], off
	global_load_dwordx4 v[128:131], v[170:171], off offset:16
	global_load_dwordx4 v[190:193], v[172:173], off offset:16 nt
	v_or_b32_e32 v168, 16, v194
	v_ashrrev_i32_e32 v169, 31, v168
	v_lshlrev_b64 v[168:169], 10, v[168:169]
	v_lshlrev_b32_e32 v144, 1, v174
	v_lshl_add_u64 v[200:201], v[168:169], 0, v[166:167]
	v_lshl_add_u64 v[174:175], v[200:201], 2, s[4:5]
	s_mov_b64 s[0:1], 0x20000
	s_and_b64 vcc, exec, s[26:27]
	v_readlane_b32 s62, v249, 11
	v_readlane_b32 s63, v249, 12
	v_readlane_b32 s64, v249, 13
	v_readlane_b32 s65, v249, 14
	v_readlane_b32 s66, v249, 15
	v_readlane_b32 s67, v249, 16
	v_readlane_b32 s68, v249, 17
	v_readlane_b32 s69, v249, 18
	v_readlane_b32 s70, v249, 19
	v_readlane_b32 s71, v249, 20
	v_readlane_b32 s72, v249, 21
	v_readlane_b32 s73, v249, 22
	v_readlane_b32 s74, v249, 23
	v_readlane_b32 s75, v249, 24
	s_waitcnt vmcnt(0)
	v_pk_fma_f32 v[124:125], v[124:125], v[132:133], v[186:187]
	v_pk_fma_f32 v[126:127], v[126:127], v[134:135], v[188:189]
	v_pk_fma_f32 v[186:187], v[122:123], v[130:131], v[192:193]
	v_pk_fma_f32 v[122:123], v[120:121], v[128:129], v[190:191]
	v_cvt_pk_bf16_f32 v120, v124, v125
	v_cvt_pk_bf16_f32 v121, v126, v127
	s_nop 0
	v_cvt_pk_bf16_f32 v122, v122, v123
	v_cvt_pk_bf16_f32 v123, v186, v187
	buffer_store_dwordx4 v[120:123], v144, s[8:11], 0 offen sc1
	global_load_dwordx4 v[124:127], v[174:175], off nt
	global_load_dwordx4 v[186:189], v[174:175], off offset:16 nt
	v_or_b32_e32 v120, 32, v194
	v_ashrrev_i32_e32 v121, 31, v120
	v_lshlrev_b64 v[120:121], 10, v[120:121]
	v_lshl_add_u64 v[190:191], v[120:121], 0, v[166:167]
	v_lshlrev_b32_e32 v121, 1, v200
	v_lshl_add_u64 v[122:123], v[190:191], 2, s[4:5]
	s_waitcnt vmcnt(1)
	v_pk_fma_f32 v[116:117], v[116:117], v[132:133], v[124:125]
	s_waitcnt vmcnt(0)
	v_pk_fma_f32 v[124:125], v[114:115], v[130:131], v[188:189]
	v_pk_fma_f32 v[114:115], v[112:113], v[128:129], v[186:187]
	v_pk_fma_f32 v[118:119], v[118:119], v[134:135], v[126:127]
	v_cvt_pk_bf16_f32 v112, v116, v117
	s_nop 0
	v_cvt_pk_bf16_f32 v113, v118, v119
	v_cvt_pk_bf16_f32 v114, v114, v115
	v_cvt_pk_bf16_f32 v115, v124, v125
	buffer_store_dwordx4 v[112:115], v121, s[8:11], 0 offen sc1
	global_load_dwordx4 v[116:119], v[122:123], off nt
	global_load_dwordx4 v[124:127], v[122:123], off offset:16 nt
	v_or_b32_e32 v112, 48, v194
	v_ashrrev_i32_e32 v113, 31, v112
	v_lshlrev_b64 v[112:113], 10, v[112:113]
	v_lshl_add_u64 v[186:187], v[112:113], 0, v[166:167]
	v_lshlrev_b32_e32 v113, 1, v190
	v_lshl_add_u64 v[114:115], v[186:187], 2, s[4:5]
	s_waitcnt vmcnt(1)
	v_pk_fma_f32 v[108:109], v[108:109], v[132:133], v[116:117]
	s_waitcnt vmcnt(0)
	v_pk_fma_f32 v[116:117], v[106:107], v[130:131], v[126:127]
	v_pk_fma_f32 v[106:107], v[104:105], v[128:129], v[124:125]
	v_pk_fma_f32 v[110:111], v[110:111], v[134:135], v[118:119]
	v_cvt_pk_bf16_f32 v104, v108, v109
	s_nop 0
	v_cvt_pk_bf16_f32 v105, v110, v111
	v_cvt_pk_bf16_f32 v106, v106, v107
	v_cvt_pk_bf16_f32 v107, v116, v117
	buffer_store_dwordx4 v[104:107], v113, s[8:11], 0 offen sc1
	global_load_dwordx4 v[108:111], v[114:115], off nt
	global_load_dwordx4 v[116:119], v[114:115], off offset:16 nt
	v_lshl_add_u64 v[104:105], v[164:165], 0, s[0:1]
	v_lshl_add_u64 v[124:125], v[104:105], 0, v[166:167]
	v_lshlrev_b32_e32 v105, 1, v186
	v_lshl_add_u64 v[106:107], v[124:125], 2, s[4:5]
	s_mov_b64 s[0:1], 0x24000
	s_waitcnt vmcnt(1)
	v_pk_fma_f32 v[100:101], v[100:101], v[132:133], v[108:109]
	s_waitcnt vmcnt(0)
	v_pk_fma_f32 v[108:109], v[98:99], v[130:131], v[118:119]
	v_pk_fma_f32 v[98:99], v[96:97], v[128:129], v[116:117]
	v_pk_fma_f32 v[102:103], v[102:103], v[134:135], v[110:111]
	v_cvt_pk_bf16_f32 v96, v100, v101
	s_nop 0
	v_cvt_pk_bf16_f32 v97, v102, v103
	v_cvt_pk_bf16_f32 v98, v98, v99
	v_cvt_pk_bf16_f32 v99, v108, v109
	buffer_store_dwordx4 v[96:99], v105, s[8:11], 0 offen sc1
	global_load_dwordx4 v[100:103], v[106:107], off nt
	global_load_dwordx4 v[108:111], v[106:107], off offset:16 nt
	v_lshl_add_u64 v[96:97], v[164:165], 0, s[0:1]
	v_lshl_add_u64 v[116:117], v[96:97], 0, v[166:167]
	v_lshlrev_b32_e32 v97, 1, v124
	v_lshl_add_u64 v[98:99], v[116:117], 2, s[4:5]
	s_mov_b64 s[0:1], 0x28000
	s_waitcnt vmcnt(1)
	v_pk_fma_f32 v[92:93], v[92:93], v[132:133], v[100:101]
	s_waitcnt vmcnt(0)
	v_pk_fma_f32 v[100:101], v[90:91], v[130:131], v[110:111]
	v_pk_fma_f32 v[90:91], v[88:89], v[128:129], v[108:109]
	v_pk_fma_f32 v[94:95], v[94:95], v[134:135], v[102:103]
	v_cvt_pk_bf16_f32 v88, v92, v93
	s_nop 0
	v_cvt_pk_bf16_f32 v89, v94, v95
	v_cvt_pk_bf16_f32 v90, v90, v91
	v_cvt_pk_bf16_f32 v91, v100, v101
	buffer_store_dwordx4 v[88:91], v97, s[8:11], 0 offen sc1
	global_load_dwordx4 v[92:95], v[98:99], off nt
	global_load_dwordx4 v[100:103], v[98:99], off offset:16 nt
	v_lshl_add_u64 v[88:89], v[164:165], 0, s[0:1]
	v_lshl_add_u64 v[108:109], v[88:89], 0, v[166:167]
	v_lshlrev_b32_e32 v89, 1, v116
	v_lshl_add_u64 v[90:91], v[108:109], 2, s[4:5]
	s_mov_b64 s[0:1], 0x2c000
	s_waitcnt vmcnt(1)
	v_pk_fma_f32 v[84:85], v[84:85], v[132:133], v[92:93]
	s_waitcnt vmcnt(0)
	v_pk_fma_f32 v[92:93], v[82:83], v[130:131], v[102:103]
	v_pk_fma_f32 v[82:83], v[80:81], v[128:129], v[100:101]
	v_pk_fma_f32 v[86:87], v[86:87], v[134:135], v[94:95]
	v_cvt_pk_bf16_f32 v80, v84, v85
	s_nop 0
	v_cvt_pk_bf16_f32 v81, v86, v87
	v_cvt_pk_bf16_f32 v82, v82, v83
	v_cvt_pk_bf16_f32 v83, v92, v93
	buffer_store_dwordx4 v[80:83], v89, s[8:11], 0 offen sc1
	global_load_dwordx4 v[84:87], v[90:91], off nt
	global_load_dwordx4 v[92:95], v[90:91], off offset:16 nt
	v_lshl_add_u64 v[80:81], v[164:165], 0, s[0:1]
	v_lshl_add_u64 v[100:101], v[80:81], 0, v[166:167]
	v_lshlrev_b32_e32 v81, 1, v108
	v_lshl_add_u64 v[82:83], v[100:101], 2, s[4:5]
	s_mov_b64 s[0:1], -1
	s_waitcnt vmcnt(1)
	v_pk_fma_f32 v[76:77], v[76:77], v[132:133], v[84:85]
	s_waitcnt vmcnt(0)
	v_pk_fma_f32 v[84:85], v[74:75], v[130:131], v[94:95]
	v_pk_fma_f32 v[74:75], v[72:73], v[128:129], v[92:93]
	v_pk_fma_f32 v[78:79], v[78:79], v[134:135], v[86:87]
	v_cvt_pk_bf16_f32 v72, v76, v77
	s_nop 0
	v_cvt_pk_bf16_f32 v73, v78, v79
	v_cvt_pk_bf16_f32 v74, v74, v75
	v_cvt_pk_bf16_f32 v75, v84, v85
	buffer_store_dwordx4 v[72:75], v81, s[8:11], 0 offen sc1
	global_load_dwordx4 v[72:75], v[82:83], off nt
	s_nop 0
	global_load_dwordx4 v[76:79], v[82:83], off offset:16 nt
	v_lshlrev_b32_e32 v81, 1, v100
	s_waitcnt vmcnt(1)
	v_pk_fma_f32 v[64:65], v[64:65], v[132:133], v[72:73]
	s_waitcnt vmcnt(0)
	v_pk_fma_f32 v[72:73], v[58:59], v[130:131], v[78:79]
	v_pk_fma_f32 v[58:59], v[56:57], v[128:129], v[76:77]
	v_pk_fma_f32 v[66:67], v[66:67], v[134:135], v[74:75]
	v_cvt_pk_bf16_f32 v56, v64, v65
	s_nop 0
	v_cvt_pk_bf16_f32 v57, v66, v67
	v_cvt_pk_bf16_f32 v58, v58, v59
	v_cvt_pk_bf16_f32 v59, v72, v73
	buffer_store_dwordx4 v[56:59], v81, s[8:11], 0 offen sc1
	global_load_dwordx4 v[72:75], v[172:173], off offset:512 nt
	global_load_dwordx4 v[64:67], v[170:171], off offset:512
	s_nop 0
	global_load_dwordx4 v[56:59], v[170:171], off offset:528
	global_load_dwordx4 v[76:79], v[172:173], off offset:528 nt
	v_or_b32_e32 v81, 0x80, v166
	v_add_lshl_u32 v84, v164, v81, 1
	s_waitcnt vmcnt(2)
	v_pk_fma_f32 v[68:69], v[68:69], v[64:65], v[72:73]
	v_pk_fma_f32 v[70:71], v[70:71], v[66:67], v[74:75]
	s_waitcnt vmcnt(0)
	v_pk_fma_f32 v[72:73], v[62:63], v[58:59], v[78:79]
	v_pk_fma_f32 v[62:63], v[60:61], v[56:57], v[76:77]
	v_cvt_pk_bf16_f32 v60, v68, v69
	v_cvt_pk_bf16_f32 v61, v70, v71
	s_nop 0
	v_cvt_pk_bf16_f32 v62, v62, v63
	v_cvt_pk_bf16_f32 v63, v72, v73
	buffer_store_dwordx4 v[60:63], v84, s[8:11], 0 offen sc1
	global_load_dwordx4 v[60:63], v[174:175], off offset:512 nt
	s_nop 0
	global_load_dwordx4 v[68:71], v[174:175], off offset:528 nt
	v_add_lshl_u32 v72, v168, v81, 1
	s_waitcnt vmcnt(1)
	v_pk_fma_f32 v[52:53], v[52:53], v[64:65], v[60:61]
	s_waitcnt vmcnt(0)
	v_pk_fma_f32 v[60:61], v[50:51], v[58:59], v[70:71]
	v_pk_fma_f32 v[50:51], v[48:49], v[56:57], v[68:69]
	v_pk_fma_f32 v[54:55], v[54:55], v[66:67], v[62:63]
	v_cvt_pk_bf16_f32 v48, v52, v53
	s_nop 0
	v_cvt_pk_bf16_f32 v49, v54, v55
	v_cvt_pk_bf16_f32 v50, v50, v51
	v_cvt_pk_bf16_f32 v51, v60, v61
	buffer_store_dwordx4 v[48:51], v72, s[8:11], 0 offen sc1
	global_load_dwordx4 v[48:51], v[122:123], off offset:512 nt
	s_nop 0
	global_load_dwordx4 v[52:55], v[122:123], off offset:528 nt
	v_add_lshl_u32 v60, v120, v81, 1
	s_waitcnt vmcnt(1)
	v_pk_fma_f32 v[44:45], v[44:45], v[64:65], v[48:49]
	s_waitcnt vmcnt(0)
	v_pk_fma_f32 v[48:49], v[42:43], v[58:59], v[54:55]
	v_pk_fma_f32 v[42:43], v[40:41], v[56:57], v[52:53]
	v_pk_fma_f32 v[46:47], v[46:47], v[66:67], v[50:51]
	v_cvt_pk_bf16_f32 v40, v44, v45
	s_nop 0
	v_cvt_pk_bf16_f32 v41, v46, v47
	v_cvt_pk_bf16_f32 v42, v42, v43
	v_cvt_pk_bf16_f32 v43, v48, v49
	buffer_store_dwordx4 v[40:43], v60, s[8:11], 0 offen sc1
	global_load_dwordx4 v[40:43], v[114:115], off offset:512 nt
	s_nop 0
	global_load_dwordx4 v[44:47], v[114:115], off offset:528 nt
	v_add_lshl_u32 v48, v112, v81, 1
	s_waitcnt vmcnt(1)
	v_pk_fma_f32 v[36:37], v[36:37], v[64:65], v[40:41]
	s_waitcnt vmcnt(0)
	v_pk_fma_f32 v[40:41], v[34:35], v[58:59], v[46:47]
	v_pk_fma_f32 v[34:35], v[32:33], v[56:57], v[44:45]
	v_pk_fma_f32 v[38:39], v[38:39], v[66:67], v[42:43]
	v_cvt_pk_bf16_f32 v32, v36, v37
	s_nop 0
	v_cvt_pk_bf16_f32 v33, v38, v39
	v_cvt_pk_bf16_f32 v34, v34, v35
	v_cvt_pk_bf16_f32 v35, v40, v41
	buffer_store_dwordx4 v[32:35], v48, s[8:11], 0 offen sc1
	global_load_dwordx4 v[32:35], v[106:107], off offset:512 nt
	s_nop 0
	global_load_dwordx4 v[36:39], v[106:107], off offset:528 nt
	v_add_lshl_u32 v40, v104, v81, 1
	s_waitcnt vmcnt(1)
	v_pk_fma_f32 v[28:29], v[28:29], v[64:65], v[32:33]
	s_waitcnt vmcnt(0)
	v_pk_fma_f32 v[32:33], v[26:27], v[58:59], v[38:39]
	v_pk_fma_f32 v[26:27], v[24:25], v[56:57], v[36:37]
	v_pk_fma_f32 v[30:31], v[30:31], v[66:67], v[34:35]
	v_cvt_pk_bf16_f32 v24, v28, v29
	s_nop 0
	v_cvt_pk_bf16_f32 v25, v30, v31
	v_cvt_pk_bf16_f32 v26, v26, v27
	v_cvt_pk_bf16_f32 v27, v32, v33
	buffer_store_dwordx4 v[24:27], v40, s[8:11], 0 offen sc1
	global_load_dwordx4 v[24:27], v[98:99], off offset:512 nt
	s_nop 0
	global_load_dwordx4 v[28:31], v[98:99], off offset:528 nt
	v_add_lshl_u32 v32, v96, v81, 1
	s_waitcnt vmcnt(1)
	v_pk_fma_f32 v[20:21], v[20:21], v[64:65], v[24:25]
	s_waitcnt vmcnt(0)
	v_pk_fma_f32 v[24:25], v[18:19], v[58:59], v[30:31]
	v_pk_fma_f32 v[18:19], v[16:17], v[56:57], v[28:29]
	v_pk_fma_f32 v[22:23], v[22:23], v[66:67], v[26:27]
	v_cvt_pk_bf16_f32 v16, v20, v21
	s_nop 0
	v_cvt_pk_bf16_f32 v17, v22, v23
	v_cvt_pk_bf16_f32 v18, v18, v19
	v_cvt_pk_bf16_f32 v19, v24, v25
	buffer_store_dwordx4 v[16:19], v32, s[8:11], 0 offen sc1
	global_load_dwordx4 v[16:19], v[90:91], off offset:512 nt
	s_nop 0
	global_load_dwordx4 v[20:23], v[90:91], off offset:528 nt
	v_add_lshl_u32 v24, v88, v81, 1
	s_waitcnt vmcnt(1)
	v_pk_fma_f32 v[12:13], v[12:13], v[64:65], v[16:17]
	s_waitcnt vmcnt(0)
	v_pk_fma_f32 v[16:17], v[10:11], v[58:59], v[22:23]
	v_pk_fma_f32 v[10:11], v[8:9], v[56:57], v[20:21]
	v_pk_fma_f32 v[14:15], v[14:15], v[66:67], v[18:19]
	v_cvt_pk_bf16_f32 v8, v12, v13
	s_nop 0
	v_cvt_pk_bf16_f32 v9, v14, v15
	v_cvt_pk_bf16_f32 v10, v10, v11
	v_cvt_pk_bf16_f32 v11, v16, v17
	buffer_store_dwordx4 v[8:11], v24, s[8:11], 0 offen sc1
	global_load_dwordx4 v[8:11], v[82:83], off offset:512 nt
	s_nop 0
	global_load_dwordx4 v[12:15], v[82:83], off offset:528 nt
	v_add_lshl_u32 v16, v80, v81, 1
	s_waitcnt vmcnt(1)
	v_pk_fma_f32 v[4:5], v[4:5], v[64:65], v[8:9]
	s_waitcnt vmcnt(0)
	v_pk_fma_f32 v[8:9], v[2:3], v[58:59], v[14:15]
	v_pk_fma_f32 v[2:3], v[0:1], v[56:57], v[12:13]
	v_pk_fma_f32 v[6:7], v[6:7], v[66:67], v[10:11]
	v_cvt_pk_bf16_f32 v0, v4, v5
	s_nop 0
	v_cvt_pk_bf16_f32 v1, v6, v7
	v_cvt_pk_bf16_f32 v2, v2, v3
	v_cvt_pk_bf16_f32 v3, v8, v9
	buffer_store_dwordx4 v[0:3], v16, s[8:11], 0 offen sc1
	s_cbranch_vccz .LBB0_768
	s_waitcnt vmcnt(0)
	s_barrier
	s_and_saveexec_b64 s[0:1], s[92:93]
	s_cbranch_execz .LBB0_764
	s_mov_b64 s[42:43], exec
	v_mbcnt_lo_u32_b32 v0, s42, 0
	v_mbcnt_hi_u32_b32 v0, s43, v0
	v_cmp_eq_u32_e32 vcc, 0, v0
	s_and_saveexec_b64 s[4:5], vcc
	s_cbranch_execz .LBB0_761
	s_ashr_i32 s15, s14, 31
	s_lshl_b64 s[60:61], s[14:15], 2
	v_readlane_b32 s62, v249, 31
	v_readlane_b32 s63, v249, 32
	s_add_u32 s60, s62, s60
	s_addc_u32 s61, s63, s61
	s_bcnt1_i32_b64 s15, s[42:43]
	v_mov_b32_e32 v1, s15
	global_atomic_add v1, v145, v1, s[60:61] sc0

.LBB0_991:
	s_lshl_b32 s8, s22, 8
	v_add_u32_e32 v180, s8, v165
	v_lshl_or_b32 v160, s58, 8, v169
	v_ashrrev_i32_e32 v181, 31, v180
	s_ashr_i32 s0, s22, 3
	v_lshlrev_b64 v[158:159], 10, v[180:181]
	v_ashrrev_i32_e32 v161, 31, v160
	v_readlane_b32 s4, v249, 44
	s_mul_hi_i32 s1, s0, 0x6000
	s_mulk_i32 s0, 0x6000
	v_lshl_add_u64 v[182:183], v[158:159], 0, v[160:161]
	v_readlane_b32 s5, v249, 45
	s_add_u32 s0, s64, s0
	s_addc_u32 s1, s65, s1
	v_lshl_add_u64 v[128:129], v[182:183], 1, s[4:5]
	global_load_dwordx4 v[176:179], v[128:129], off nt
	v_lshl_add_u64 v[156:157], v[160:161], 2, s[0:1]
	global_load_dwordx4 v[132:135], v[156:157], off
	global_load_dwordx4 v[128:131], v[156:157], off offset:16
	v_or_b32_e32 v162, 16, v180
	v_ashrrev_i32_e32 v163, 31, v162
	v_lshlrev_b64 v[162:163], 10, v[162:163]
	v_lshlrev_b32_e32 v181, 1, v182
	v_lshl_add_u64 v[182:183], v[162:163], 0, v[160:161]
	v_lshl_add_u64 v[184:185], v[182:183], 1, s[4:5]
	s_mov_b64 s[0:1], -1
	s_and_b64 vcc, exec, s[38:39]
	s_waitcnt vmcnt(0)
	v_lshlrev_b32_e32 v186, 16, v176
	v_and_b32_e32 v187, 0xffff0000, v176
	v_lshlrev_b32_e32 v176, 16, v177
	v_and_b32_e32 v177, 0xffff0000, v177
	v_lshlrev_b32_e32 v188, 16, v178
	v_and_b32_e32 v189, 0xffff0000, v178
	v_lshlrev_b32_e32 v178, 16, v179
	v_and_b32_e32 v179, 0xffff0000, v179
	v_pk_fma_f32 v[126:127], v[126:127], v[134:135], v[176:177]
	v_pk_fma_f32 v[176:177], v[122:123], v[130:131], v[178:179]
	v_pk_fma_f32 v[122:123], v[120:121], v[128:129], v[188:189]
	v_pk_fma_f32 v[124:125], v[124:125], v[132:133], v[186:187]
	s_nop 0
	v_cvt_pk_bf16_f32 v120, v124, v125
	v_cvt_pk_bf16_f32 v121, v126, v127
	v_cvt_pk_bf16_f32 v122, v122, v123
	v_cvt_pk_bf16_f32 v123, v176, v177
	buffer_store_dwordx4 v[120:123], v181, s[16:19], 0 offen sc1
	global_load_dwordx4 v[122:125], v[184:185], off nt
	v_lshlrev_b32_e32 v181, 1, v182
	v_or_b32_e32 v120, 32, v180
	v_ashrrev_i32_e32 v121, 31, v120
	v_lshlrev_b64 v[120:121], 10, v[120:121]
	v_lshl_add_u64 v[126:127], v[120:121], 0, v[160:161]
	v_lshl_add_u64 v[176:177], v[126:127], 1, s[4:5]
	s_waitcnt vmcnt(0)
	v_lshlrev_b32_e32 v178, 16, v122
	v_and_b32_e32 v179, 0xffff0000, v122
	v_lshlrev_b32_e32 v122, 16, v123
	v_and_b32_e32 v123, 0xffff0000, v123
	v_lshlrev_b32_e32 v182, 16, v124
	v_and_b32_e32 v183, 0xffff0000, v124
	v_lshlrev_b32_e32 v124, 16, v125
	v_and_b32_e32 v125, 0xffff0000, v125
	v_pk_fma_f32 v[118:119], v[118:119], v[134:135], v[122:123]
	v_pk_fma_f32 v[122:123], v[114:115], v[130:131], v[124:125]
	v_pk_fma_f32 v[114:115], v[112:113], v[128:129], v[182:183]
	v_pk_fma_f32 v[116:117], v[116:117], v[132:133], v[178:179]
	s_nop 0
	v_cvt_pk_bf16_f32 v112, v116, v117
	v_cvt_pk_bf16_f32 v113, v118, v119
	v_cvt_pk_bf16_f32 v114, v114, v115
	v_cvt_pk_bf16_f32 v115, v122, v123
	buffer_store_dwordx4 v[112:115], v181, s[16:19], 0 offen sc1
	global_load_dwordx4 v[114:117], v[176:177], off nt
	v_lshlrev_b32_e32 v176, 1, v126
	v_or_b32_e32 v112, 48, v180
	v_ashrrev_i32_e32 v113, 31, v112
	v_lshlrev_b64 v[112:113], 10, v[112:113]
	v_lshl_add_u64 v[118:119], v[112:113], 0, v[160:161]
	v_lshl_add_u64 v[122:123], v[118:119], 1, s[4:5]
	s_waitcnt vmcnt(0)
	v_lshlrev_b32_e32 v124, 16, v114
	v_and_b32_e32 v125, 0xffff0000, v114
	v_lshlrev_b32_e32 v114, 16, v115
	v_and_b32_e32 v115, 0xffff0000, v115
	v_lshlrev_b32_e32 v126, 16, v116
	v_and_b32_e32 v127, 0xffff0000, v116
	v_lshlrev_b32_e32 v116, 16, v117
	v_and_b32_e32 v117, 0xffff0000, v117
	v_pk_fma_f32 v[110:111], v[110:111], v[134:135], v[114:115]
	v_pk_fma_f32 v[114:115], v[106:107], v[130:131], v[116:117]
	v_pk_fma_f32 v[106:107], v[104:105], v[128:129], v[126:127]
	v_pk_fma_f32 v[108:109], v[108:109], v[132:133], v[124:125]
	s_nop 0
	v_cvt_pk_bf16_f32 v104, v108, v109
	v_cvt_pk_bf16_f32 v105, v110, v111
	v_cvt_pk_bf16_f32 v106, v106, v107
	v_cvt_pk_bf16_f32 v107, v114, v115
	buffer_store_dwordx4 v[104:107], v176, s[16:19], 0 offen sc1
	global_load_dwordx4 v[106:109], v[122:123], off nt
	v_lshlrev_b32_e32 v122, 1, v118
	v_lshl_add_u64 v[104:105], v[158:159], 0, s[42:43]
	v_lshl_add_u64 v[110:111], v[104:105], 0, v[160:161]
	v_lshl_add_u64 v[114:115], v[110:111], 1, s[4:5]
	s_waitcnt vmcnt(0)
	v_lshlrev_b32_e32 v116, 16, v106
	v_and_b32_e32 v117, 0xffff0000, v106
	v_lshlrev_b32_e32 v106, 16, v107
	v_and_b32_e32 v107, 0xffff0000, v107
	v_lshlrev_b32_e32 v118, 16, v108
	v_and_b32_e32 v119, 0xffff0000, v108
	v_lshlrev_b32_e32 v108, 16, v109
	v_and_b32_e32 v109, 0xffff0000, v109
	v_pk_fma_f32 v[102:103], v[102:103], v[134:135], v[106:107]
	v_pk_fma_f32 v[106:107], v[98:99], v[130:131], v[108:109]
	v_pk_fma_f32 v[98:99], v[96:97], v[128:129], v[118:119]
	v_pk_fma_f32 v[100:101], v[100:101], v[132:133], v[116:117]
	s_nop 0
	v_cvt_pk_bf16_f32 v96, v100, v101
	v_cvt_pk_bf16_f32 v97, v102, v103
	v_cvt_pk_bf16_f32 v98, v98, v99
	v_cvt_pk_bf16_f32 v99, v106, v107
	buffer_store_dwordx4 v[96:99], v122, s[16:19], 0 offen sc1
	global_load_dwordx4 v[98:101], v[114:115], off nt
	v_lshlrev_b32_e32 v114, 1, v110
	v_lshl_add_u64 v[96:97], v[158:159], 0, s[44:45]
	v_lshl_add_u64 v[102:103], v[96:97], 0, v[160:161]
	v_lshl_add_u64 v[106:107], v[102:103], 1, s[4:5]
	s_waitcnt vmcnt(0)
	v_lshlrev_b32_e32 v108, 16, v98
	v_and_b32_e32 v109, 0xffff0000, v98
	v_lshlrev_b32_e32 v98, 16, v99
	v_and_b32_e32 v99, 0xffff0000, v99
	v_lshlrev_b32_e32 v110, 16, v100
	v_and_b32_e32 v111, 0xffff0000, v100
	v_lshlrev_b32_e32 v100, 16, v101
	v_and_b32_e32 v101, 0xffff0000, v101
	v_pk_fma_f32 v[94:95], v[94:95], v[134:135], v[98:99]
	v_pk_fma_f32 v[98:99], v[90:91], v[130:131], v[100:101]
	v_pk_fma_f32 v[90:91], v[88:89], v[128:129], v[110:111]
	v_pk_fma_f32 v[92:93], v[92:93], v[132:133], v[108:109]
	s_nop 0
	v_cvt_pk_bf16_f32 v88, v92, v93
	v_cvt_pk_bf16_f32 v89, v94, v95
	v_cvt_pk_bf16_f32 v90, v90, v91
	v_cvt_pk_bf16_f32 v91, v98, v99
	buffer_store_dwordx4 v[88:91], v114, s[16:19], 0 offen sc1
	global_load_dwordx4 v[90:93], v[106:107], off nt
	v_lshlrev_b32_e32 v106, 1, v102
	v_lshl_add_u64 v[88:89], v[158:159], 0, s[46:47]
	v_lshl_add_u64 v[94:95], v[88:89], 0, v[160:161]
	v_lshl_add_u64 v[98:99], v[94:95], 1, s[4:5]
	s_waitcnt vmcnt(0)
	v_lshlrev_b32_e32 v100, 16, v90
	v_and_b32_e32 v101, 0xffff0000, v90
	v_lshlrev_b32_e32 v90, 16, v91
	v_and_b32_e32 v91, 0xffff0000, v91
	v_lshlrev_b32_e32 v102, 16, v92
	v_and_b32_e32 v103, 0xffff0000, v92
	v_lshlrev_b32_e32 v92, 16, v93
	v_and_b32_e32 v93, 0xffff0000, v93
	v_pk_fma_f32 v[86:87], v[86:87], v[134:135], v[90:91]
	v_pk_fma_f32 v[90:91], v[82:83], v[130:131], v[92:93]
	v_pk_fma_f32 v[82:83], v[80:81], v[128:129], v[102:103]
	v_pk_fma_f32 v[84:85], v[84:85], v[132:133], v[100:101]
	s_nop 0
	v_cvt_pk_bf16_f32 v80, v84, v85
	v_cvt_pk_bf16_f32 v81, v86, v87
	v_cvt_pk_bf16_f32 v82, v82, v83
	v_cvt_pk_bf16_f32 v83, v90, v91
	buffer_store_dwordx4 v[80:83], v106, s[16:19], 0 offen sc1
	global_load_dwordx4 v[82:85], v[98:99], off nt
	v_lshlrev_b32_e32 v98, 1, v94
	v_lshl_add_u64 v[80:81], v[158:159], 0, s[48:49]
	v_lshl_add_u64 v[86:87], v[80:81], 0, v[160:161]
	v_lshl_add_u64 v[90:91], v[86:87], 1, s[4:5]
	s_waitcnt vmcnt(0)
	v_lshlrev_b32_e32 v92, 16, v82
	v_and_b32_e32 v93, 0xffff0000, v82
	v_lshlrev_b32_e32 v82, 16, v83
	v_and_b32_e32 v83, 0xffff0000, v83
	v_lshlrev_b32_e32 v94, 16, v84
	v_and_b32_e32 v95, 0xffff0000, v84
	v_lshlrev_b32_e32 v84, 16, v85
	v_and_b32_e32 v85, 0xffff0000, v85
	v_pk_fma_f32 v[78:79], v[78:79], v[134:135], v[82:83]
	v_pk_fma_f32 v[82:83], v[74:75], v[130:131], v[84:85]
	v_pk_fma_f32 v[74:75], v[72:73], v[128:129], v[94:95]
	v_pk_fma_f32 v[76:77], v[76:77], v[132:133], v[92:93]
	s_nop 0
	v_cvt_pk_bf16_f32 v72, v76, v77
	v_cvt_pk_bf16_f32 v73, v78, v79
	v_cvt_pk_bf16_f32 v74, v74, v75
	v_cvt_pk_bf16_f32 v75, v82, v83
	buffer_store_dwordx4 v[72:75], v98, s[16:19], 0 offen sc1
	global_load_dwordx4 v[74:77], v[90:91], off nt
	s_waitcnt vmcnt(0)
	v_lshlrev_b32_e32 v84, 16, v74
	v_or_b32_e32 v72, 0x80, v160
	v_ashrrev_i32_e32 v73, 31, v72
	v_lshl_add_u64 v[78:79], v[158:159], 0, v[72:73]
	v_lshl_add_u64 v[82:83], v[78:79], 1, s[4:5]
	v_lshlrev_b32_e32 v79, 1, v86
	v_and_b32_e32 v85, 0xffff0000, v74
	v_lshlrev_b32_e32 v74, 16, v75
	v_and_b32_e32 v75, 0xffff0000, v75
	v_lshlrev_b32_e32 v86, 16, v76
	v_and_b32_e32 v87, 0xffff0000, v76
	v_lshlrev_b32_e32 v76, 16, v77
	v_and_b32_e32 v77, 0xffff0000, v77
	v_pk_fma_f32 v[70:71], v[70:71], v[134:135], v[74:75]
	v_pk_fma_f32 v[74:75], v[66:67], v[130:131], v[76:77]
	v_pk_fma_f32 v[66:67], v[64:65], v[128:129], v[86:87]
	v_pk_fma_f32 v[68:69], v[68:69], v[132:133], v[84:85]
	v_lshlrev_b32_e32 v90, 1, v78
	v_cvt_pk_bf16_f32 v64, v68, v69
	v_cvt_pk_bf16_f32 v65, v70, v71
	v_cvt_pk_bf16_f32 v66, v66, v67
	v_cvt_pk_bf16_f32 v67, v74, v75
	buffer_store_dwordx4 v[64:67], v79, s[16:19], 0 offen sc1
	global_load_dwordx4 v[74:77], v[82:83], off nt
	global_load_dwordx4 v[68:71], v[156:157], off offset:512
	s_nop 0
	global_load_dwordx4 v[64:67], v[156:157], off offset:528
	v_lshl_add_u64 v[78:79], v[162:163], 0, v[72:73]
	v_lshl_add_u64 v[82:83], v[78:79], 1, s[4:5]
	v_lshlrev_b32_e32 v78, 1, v78
	s_waitcnt vmcnt(2)
	v_lshlrev_b32_e32 v84, 16, v74
	v_and_b32_e32 v85, 0xffff0000, v74
	v_lshlrev_b32_e32 v74, 16, v75
	v_and_b32_e32 v75, 0xffff0000, v75
	v_lshlrev_b32_e32 v86, 16, v76
	v_and_b32_e32 v87, 0xffff0000, v76
	v_lshlrev_b32_e32 v76, 16, v77
	v_and_b32_e32 v77, 0xffff0000, v77
	s_waitcnt vmcnt(1)
	v_pk_fma_f32 v[62:63], v[62:63], v[70:71], v[74:75]
	s_waitcnt vmcnt(0)
	v_pk_fma_f32 v[74:75], v[58:59], v[66:67], v[76:77]
	v_pk_fma_f32 v[58:59], v[56:57], v[64:65], v[86:87]
	v_pk_fma_f32 v[60:61], v[60:61], v[68:69], v[84:85]
	s_nop 0
	v_cvt_pk_bf16_f32 v56, v60, v61
	v_cvt_pk_bf16_f32 v57, v62, v63
	v_cvt_pk_bf16_f32 v58, v58, v59
	v_cvt_pk_bf16_f32 v59, v74, v75
	buffer_store_dwordx4 v[56:59], v90, s[16:19], 0 offen sc1
	global_load_dwordx4 v[56:59], v[82:83], off nt
	v_lshl_add_u64 v[60:61], v[120:121], 0, v[72:73]
	v_lshl_add_u64 v[62:63], v[60:61], 1, s[4:5]
	v_lshlrev_b32_e32 v60, 1, v60
	s_waitcnt vmcnt(0)
	v_lshlrev_b32_e32 v74, 16, v56
	v_and_b32_e32 v75, 0xffff0000, v56
	v_lshlrev_b32_e32 v56, 16, v57
	v_and_b32_e32 v57, 0xffff0000, v57
	v_lshlrev_b32_e32 v76, 16, v58
	v_and_b32_e32 v77, 0xffff0000, v58
	v_lshlrev_b32_e32 v58, 16, v59
	v_and_b32_e32 v59, 0xffff0000, v59
	v_pk_fma_f32 v[54:55], v[54:55], v[70:71], v[56:57]
	v_pk_fma_f32 v[56:57], v[50:51], v[66:67], v[58:59]
	v_pk_fma_f32 v[50:51], v[48:49], v[64:65], v[76:77]
	v_pk_fma_f32 v[52:53], v[52:53], v[68:69], v[74:75]
	s_nop 0
	v_cvt_pk_bf16_f32 v48, v52, v53
	v_cvt_pk_bf16_f32 v49, v54, v55
	v_cvt_pk_bf16_f32 v50, v50, v51
	v_cvt_pk_bf16_f32 v51, v56, v57
	buffer_store_dwordx4 v[48:51], v78, s[16:19], 0 offen sc1
	global_load_dwordx4 v[48:51], v[62:63], off nt
	v_lshl_add_u64 v[52:53], v[112:113], 0, v[72:73]
	v_lshl_add_u64 v[54:55], v[52:53], 1, s[4:5]
	v_lshlrev_b32_e32 v52, 1, v52
	s_waitcnt vmcnt(0)
	v_lshlrev_b32_e32 v56, 16, v48
	v_and_b32_e32 v57, 0xffff0000, v48
	v_lshlrev_b32_e32 v48, 16, v49
	v_and_b32_e32 v49, 0xffff0000, v49
	v_lshlrev_b32_e32 v58, 16, v50
	v_and_b32_e32 v59, 0xffff0000, v50
	v_lshlrev_b32_e32 v50, 16, v51
	v_and_b32_e32 v51, 0xffff0000, v51
	v_pk_fma_f32 v[46:47], v[46:47], v[70:71], v[48:49]
	v_pk_fma_f32 v[48:49], v[42:43], v[66:67], v[50:51]
	v_pk_fma_f32 v[42:43], v[40:41], v[64:65], v[58:59]
	v_pk_fma_f32 v[44:45], v[44:45], v[68:69], v[56:57]
	s_nop 0
	v_cvt_pk_bf16_f32 v40, v44, v45
	v_cvt_pk_bf16_f32 v41, v46, v47
	v_cvt_pk_bf16_f32 v42, v42, v43
	v_cvt_pk_bf16_f32 v43, v48, v49
	buffer_store_dwordx4 v[40:43], v60, s[16:19], 0 offen sc1
	global_load_dwordx4 v[40:43], v[54:55], off nt
	v_lshl_add_u64 v[44:45], v[104:105], 0, v[72:73]
	v_lshl_add_u64 v[46:47], v[44:45], 1, s[4:5]
	v_lshlrev_b32_e32 v44, 1, v44
	s_waitcnt vmcnt(0)
	v_lshlrev_b32_e32 v48, 16, v40
	v_and_b32_e32 v49, 0xffff0000, v40
	v_lshlrev_b32_e32 v40, 16, v41
	v_and_b32_e32 v41, 0xffff0000, v41
	v_lshlrev_b32_e32 v50, 16, v42
	v_and_b32_e32 v51, 0xffff0000, v42
	v_lshlrev_b32_e32 v42, 16, v43
	v_and_b32_e32 v43, 0xffff0000, v43
	v_pk_fma_f32 v[38:39], v[38:39], v[70:71], v[40:41]
	v_pk_fma_f32 v[40:41], v[34:35], v[66:67], v[42:43]
	v_pk_fma_f32 v[34:35], v[32:33], v[64:65], v[50:51]
	v_pk_fma_f32 v[36:37], v[36:37], v[68:69], v[48:49]
	s_nop 0
	v_cvt_pk_bf16_f32 v32, v36, v37
	v_cvt_pk_bf16_f32 v33, v38, v39
	v_cvt_pk_bf16_f32 v34, v34, v35
	v_cvt_pk_bf16_f32 v35, v40, v41
	buffer_store_dwordx4 v[32:35], v52, s[16:19], 0 offen sc1
	global_load_dwordx4 v[32:35], v[46:47], off nt
	v_lshl_add_u64 v[36:37], v[96:97], 0, v[72:73]
	v_lshl_add_u64 v[38:39], v[36:37], 1, s[4:5]
	v_lshlrev_b32_e32 v36, 1, v36
	s_waitcnt vmcnt(0)
	v_lshlrev_b32_e32 v40, 16, v32
	v_and_b32_e32 v41, 0xffff0000, v32
	v_lshlrev_b32_e32 v32, 16, v33
	v_and_b32_e32 v33, 0xffff0000, v33
	v_lshlrev_b32_e32 v42, 16, v34
	v_and_b32_e32 v43, 0xffff0000, v34
	v_lshlrev_b32_e32 v34, 16, v35
	v_and_b32_e32 v35, 0xffff0000, v35
	v_pk_fma_f32 v[30:31], v[30:31], v[70:71], v[32:33]
	v_pk_fma_f32 v[32:33], v[26:27], v[66:67], v[34:35]
	v_pk_fma_f32 v[26:27], v[24:25], v[64:65], v[42:43]
	v_pk_fma_f32 v[28:29], v[28:29], v[68:69], v[40:41]
	s_nop 0
	v_cvt_pk_bf16_f32 v24, v28, v29
	v_cvt_pk_bf16_f32 v25, v30, v31
	v_cvt_pk_bf16_f32 v26, v26, v27
	v_cvt_pk_bf16_f32 v27, v32, v33
	buffer_store_dwordx4 v[24:27], v44, s[16:19], 0 offen sc1
	global_load_dwordx4 v[24:27], v[38:39], off nt
	v_lshl_add_u64 v[28:29], v[88:89], 0, v[72:73]
	v_lshl_add_u64 v[30:31], v[28:29], 1, s[4:5]
	v_lshlrev_b32_e32 v28, 1, v28
	s_waitcnt vmcnt(0)
	v_lshlrev_b32_e32 v32, 16, v24
	v_and_b32_e32 v33, 0xffff0000, v24
	v_lshlrev_b32_e32 v24, 16, v25
	v_and_b32_e32 v25, 0xffff0000, v25
	v_lshlrev_b32_e32 v34, 16, v26
	v_and_b32_e32 v35, 0xffff0000, v26
	v_lshlrev_b32_e32 v26, 16, v27
	v_and_b32_e32 v27, 0xffff0000, v27
	v_pk_fma_f32 v[22:23], v[22:23], v[70:71], v[24:25]
	v_pk_fma_f32 v[24:25], v[18:19], v[66:67], v[26:27]
	v_pk_fma_f32 v[18:19], v[16:17], v[64:65], v[34:35]
	v_pk_fma_f32 v[20:21], v[20:21], v[68:69], v[32:33]
	s_nop 0
	v_cvt_pk_bf16_f32 v16, v20, v21
	v_cvt_pk_bf16_f32 v17, v22, v23
	v_cvt_pk_bf16_f32 v18, v18, v19
	v_cvt_pk_bf16_f32 v19, v24, v25
	buffer_store_dwordx4 v[16:19], v36, s[16:19], 0 offen sc1
	global_load_dwordx4 v[16:19], v[30:31], off nt
	v_lshl_add_u64 v[20:21], v[80:81], 0, v[72:73]
	v_lshl_add_u64 v[22:23], v[20:21], 1, s[4:5]
	s_waitcnt vmcnt(0)
	v_lshlrev_b32_e32 v24, 16, v16
	v_and_b32_e32 v25, 0xffff0000, v16
	v_lshlrev_b32_e32 v16, 16, v17
	v_and_b32_e32 v17, 0xffff0000, v17
	v_lshlrev_b32_e32 v26, 16, v18
	v_and_b32_e32 v27, 0xffff0000, v18
	v_lshlrev_b32_e32 v18, 16, v19
	v_and_b32_e32 v19, 0xffff0000, v19
	v_pk_fma_f32 v[14:15], v[14:15], v[70:71], v[16:17]
	v_pk_fma_f32 v[16:17], v[10:11], v[66:67], v[18:19]
	v_pk_fma_f32 v[10:11], v[8:9], v[64:65], v[26:27]
	v_pk_fma_f32 v[12:13], v[12:13], v[68:69], v[24:25]
	s_nop 0
	v_cvt_pk_bf16_f32 v8, v12, v13
	v_cvt_pk_bf16_f32 v9, v14, v15
	v_cvt_pk_bf16_f32 v10, v10, v11
	v_cvt_pk_bf16_f32 v11, v16, v17
	buffer_store_dwordx4 v[8:11], v28, s[16:19], 0 offen sc1
	global_load_dwordx4 v[8:11], v[22:23], off nt
	v_lshlrev_b32_e32 v16, 1, v20
	s_waitcnt vmcnt(0)
	v_lshlrev_b32_e32 v12, 16, v8
	v_and_b32_e32 v13, 0xffff0000, v8
	v_lshlrev_b32_e32 v8, 16, v9
	v_and_b32_e32 v9, 0xffff0000, v9
	v_lshlrev_b32_e32 v14, 16, v10
	v_and_b32_e32 v15, 0xffff0000, v10
	v_lshlrev_b32_e32 v10, 16, v11
	v_and_b32_e32 v11, 0xffff0000, v11
	v_pk_fma_f32 v[6:7], v[6:7], v[70:71], v[8:9]
	v_pk_fma_f32 v[8:9], v[2:3], v[66:67], v[10:11]
	v_pk_fma_f32 v[2:3], v[0:1], v[64:65], v[14:15]
	v_pk_fma_f32 v[4:5], v[4:5], v[68:69], v[12:13]
	s_nop 0
	v_cvt_pk_bf16_f32 v0, v4, v5
	v_cvt_pk_bf16_f32 v1, v6, v7
	v_cvt_pk_bf16_f32 v2, v2, v3
	v_cvt_pk_bf16_f32 v3, v8, v9
	buffer_store_dwordx4 v[0:3], v16, s[16:19], 0 offen sc1
	s_cbranch_vccz .LBB0_1002
	s_waitcnt vmcnt(0)
	s_barrier
	s_and_saveexec_b64 s[0:1], s[92:93]
	s_cbranch_execz .LBB0_998
	s_mov_b64 s[6:7], exec
	v_mbcnt_lo_u32_b32 v0, s6, 0
	v_mbcnt_hi_u32_b32 v0, s7, v0
	v_cmp_eq_u32_e32 vcc, 0, v0
	s_and_saveexec_b64 s[4:5], vcc
	s_cbranch_execz .LBB0_995
	s_ashr_i32 s23, s22, 31
	s_lshl_b64 s[10:11], s[22:23], 2
	s_add_u32 s10, s33, s10
	s_addc_u32 s11, s56, s11
	s_bcnt1_i32_b64 s6, s[6:7]
	v_mov_b32_e32 v1, s6
	global_atomic_add v1, v139, v1, s[10:11] sc0

.LBB0_1005:
	v_cndmask_b32_e64 v17, 0, 1, s[54:55]
	v_or_b32_e32 v16, s23, v90
	v_cmp_ne_u32_e64 s[4:5], 1, v17
	v_ashrrev_i32_e32 v17, 31, v16
	v_or_b32_e32 v18, 1, v16
	v_or_b32_e32 v20, 2, v16
	v_or_b32_e32 v24, 3, v16
	v_lshlrev_b64 v[22:23], 11, v[16:17]
	v_ashrrev_i32_e32 v19, 31, v18
	v_ashrrev_i32_e32 v21, 31, v20
	v_ashrrev_i32_e32 v25, 31, v24
	v_lshlrev_b64 v[16:17], 12, v[16:17]
	v_lshl_add_u64 v[28:29], v[146:147], 0, v[22:23]
	v_lshlrev_b64 v[32:33], 11, v[18:19]
	v_lshlrev_b64 v[34:35], 11, v[20:21]
	v_lshlrev_b64 v[36:37], 11, v[24:25]
	v_lshl_add_u64 v[22:23], v[148:149], 0, v[16:17]
	v_lshlrev_b64 v[16:17], 12, v[18:19]
	v_lshlrev_b64 v[38:39], 12, v[24:25]
	global_load_dwordx4 v[24:27], v[28:29], off offset:1024
	s_nop 0
	global_load_dwordx4 v[28:31], v[28:29], off
	v_lshl_add_u64 v[32:33], v[146:147], 0, v[32:33]
	v_lshlrev_b64 v[18:19], 12, v[20:21]
	v_lshl_add_u64 v[34:35], v[146:147], 0, v[34:35]
	v_lshl_add_u64 v[36:37], v[146:147], 0, v[36:37]
	v_lshl_add_u64 v[20:21], v[148:149], 0, v[16:17]
	v_lshl_add_u64 v[16:17], v[148:149], 0, v[38:39]
	global_load_dwordx4 v[38:41], v[32:33], off offset:1024
	global_load_dwordx4 v[46:49], v[32:33], off
	global_load_dwordx4 v[80:83], v[34:35], off offset:1024
	global_load_dwordx4 v[52:55], v[34:35], off
	global_load_dwordx4 v[92:95], v[36:37], off offset:1024
	global_load_dwordx4 v[96:99], v[36:37], off
	v_lshl_add_u64 v[18:19], v[148:149], 0, v[18:19]
	s_mov_b32 s23, 4
	s_mov_b64 s[54:55], 0
	s_waitcnt vmcnt(7)
	v_lshlrev_b32_e32 v70, 16, v24
	s_waitcnt vmcnt(6)
	v_lshlrev_b32_e32 v60, 16, v28
	v_lshlrev_b32_e32 v62, 16, v29
	v_and_b32_e32 v65, 0xffff0000, v31
	v_and_b32_e32 v64, 0xffff0000, v30
	v_lshlrev_b32_e32 v72, 16, v25
	v_and_b32_e32 v61, 0xffff0000, v28
	v_and_b32_e32 v63, 0xffff0000, v29
	v_lshlrev_b32_e32 v101, 16, v31
	v_lshlrev_b32_e32 v100, 16, v30
	v_and_b32_e32 v71, 0xffff0000, v24
	v_and_b32_e32 v73, 0xffff0000, v25
	v_mul_f32_e32 v102, v60, v60
	v_mul_f32_e32 v104, v62, v62
	v_pk_mul_f32 v[106:107], v[64:65], v[64:65]
	v_mul_f32_e32 v108, v70, v70
	v_mul_f32_e32 v110, v72, v72
	s_waitcnt vmcnt(5)
	v_lshlrev_b32_e32 v42, 16, v40
	v_and_b32_e32 v43, 0xffff0000, v40
	v_lshlrev_b32_e32 v44, 16, v41
	v_and_b32_e32 v45, 0xffff0000, v41
	s_waitcnt vmcnt(4)
	v_lshlrev_b32_e32 v66, 16, v46
	v_lshlrev_b32_e32 v68, 16, v47
	v_and_b32_e32 v75, 0xffff0000, v49
	v_and_b32_e32 v74, 0xffff0000, v48
	v_lshlrev_b32_e32 v76, 16, v38
	v_and_b32_e32 v77, 0xffff0000, v38
	v_lshlrev_b32_e32 v78, 16, v39
	s_waitcnt vmcnt(2)
	v_lshlrev_b32_e32 v50, 16, v52
	v_and_b32_e32 v51, 0xffff0000, v52
	v_lshlrev_b32_e32 v52, 16, v53
	v_lshlrev_b32_e32 v117, 16, v55
	v_lshlrev_b32_e32 v116, 16, v54
	v_and_b32_e32 v55, 0xffff0000, v55
	v_and_b32_e32 v54, 0xffff0000, v54
	v_lshlrev_b32_e32 v56, 16, v80
	s_waitcnt vmcnt(0)
	v_lshlrev_b32_e32 v34, 16, v96
	v_lshlrev_b32_e32 v38, 16, v97
	v_and_b32_e32 v41, 0xffff0000, v99
	v_and_b32_e32 v40, 0xffff0000, v98
	v_lshlrev_b32_e32 v32, 16, v26
	v_and_b32_e32 v33, 0xffff0000, v26
	v_lshlrev_b32_e32 v36, 16, v27
	v_and_b32_e32 v37, 0xffff0000, v27
	v_and_b32_e32 v67, 0xffff0000, v46
	v_and_b32_e32 v69, 0xffff0000, v47
	v_lshlrev_b32_e32 v115, 16, v49
	v_lshlrev_b32_e32 v114, 16, v48
	v_and_b32_e32 v79, 0xffff0000, v39
	v_and_b32_e32 v53, 0xffff0000, v53
	v_and_b32_e32 v57, 0xffff0000, v80
	v_lshlrev_b32_e32 v58, 16, v81
	v_lshlrev_b32_e32 v24, 16, v94
	v_and_b32_e32 v25, 0xffff0000, v94
	v_lshlrev_b32_e32 v26, 16, v95
	v_and_b32_e32 v27, 0xffff0000, v95
	v_and_b32_e32 v35, 0xffff0000, v96
	v_and_b32_e32 v39, 0xffff0000, v97
	v_lshlrev_b32_e32 v95, 16, v99
	v_lshlrev_b32_e32 v94, 16, v98
	v_lshlrev_b32_e32 v46, 16, v92
	v_and_b32_e32 v47, 0xffff0000, v92
	v_lshlrev_b32_e32 v48, 16, v93
	v_and_b32_e32 v49, 0xffff0000, v93
	v_mov_b32_e32 v92, v100
	v_mov_b32_e32 v93, v64
	v_mov_b32_e32 v64, v101
	v_pk_fma_f32 v[96:97], v[60:61], v[60:61], v[102:103] op_sel_hi:[1,1,0]
	v_pk_fma_f32 v[98:99], v[62:63], v[62:63], v[104:105] op_sel_hi:[1,1,0]
	v_pk_fma_f32 v[100:101], v[100:101], v[100:101], v[106:107]
	v_pk_fma_f32 v[102:103], v[70:71], v[70:71], v[108:109] op_sel_hi:[1,1,0]
	v_pk_fma_f32 v[104:105], v[72:73], v[72:73], v[110:111] op_sel_hi:[1,1,0]
	v_mul_f32_e32 v106, v66, v66
	v_mul_f32_e32 v108, v68, v68
	v_pk_mul_f32 v[110:111], v[74:75], v[74:75]
	v_mul_f32_e32 v118, v76, v76
	v_mul_f32_e32 v120, v78, v78
	v_mul_f32_e32 v124, v50, v50
	v_mul_f32_e32 v126, v52, v52
	v_pk_mul_f32 v[128:129], v[54:55], v[54:55]
	v_mul_f32_e32 v130, v56, v56
	v_mul_f32_e32 v156, v34, v34
	v_mul_f32_e32 v158, v38, v38
	v_pk_mul_f32 v[160:161], v[40:41], v[40:41]
	v_lshlrev_b32_e32 v28, 16, v82
	v_and_b32_e32 v29, 0xffff0000, v82
	v_lshlrev_b32_e32 v30, 16, v83
	v_and_b32_e32 v31, 0xffff0000, v83
	v_and_b32_e32 v59, 0xffff0000, v81
	v_mul_f32_e32 v132, v58, v58
	v_mul_f32_e32 v162, v46, v46
	v_mul_f32_e32 v176, v48, v48
	v_mov_b32_e32 v180, v114
	v_mov_b32_e32 v181, v74
	v_mov_b32_e32 v74, v115
	v_mov_b32_e32 v82, v116
	v_mov_b32_e32 v83, v54
	v_mov_b32_e32 v54, v117
	v_mov_b32_e32 v80, v94
	v_mov_b32_e32 v81, v40
	v_mov_b32_e32 v40, v95
	v_pk_add_f32 v[100:101], v[100:101], v[100:101] op_sel_hi:[0,1]
	v_mul_f32_e32 v102, v36, v36
	v_mul_f32_e32 v104, v37, v37
	v_pk_add_f32 v[96:97], v[96:97], v[98:99]
	v_pk_fma_f32 v[98:99], v[66:67], v[66:67], v[106:107] op_sel_hi:[1,1,0]
	v_pk_fma_f32 v[106:107], v[68:69], v[68:69], v[108:109] op_sel_hi:[1,1,0]
	v_pk_fma_f32 v[108:109], v[114:115], v[114:115], v[110:111]
	v_pk_fma_f32 v[110:111], v[76:77], v[76:77], v[118:119] op_sel_hi:[1,1,0]
	v_pk_fma_f32 v[114:115], v[78:79], v[78:79], v[120:121] op_sel_hi:[1,1,0]
	v_pk_fma_f32 v[118:119], v[50:51], v[50:51], v[124:125] op_sel_hi:[1,1,0]
	v_pk_fma_f32 v[120:121], v[52:53], v[52:53], v[126:127] op_sel_hi:[1,1,0]
	v_pk_fma_f32 v[116:117], v[116:117], v[116:117], v[128:129]
	v_pk_fma_f32 v[124:125], v[56:57], v[56:57], v[130:131] op_sel_hi:[1,1,0]
	v_pk_fma_f32 v[128:129], v[34:35], v[34:35], v[156:157] op_sel_hi:[1,1,0]
	v_pk_fma_f32 v[130:131], v[38:39], v[38:39], v[158:159] op_sel_hi:[1,1,0]
	v_pk_fma_f32 v[94:95], v[94:95], v[94:95], v[160:161]
	v_mul_f32_e32 v112, v32, v32
	v_pk_fma_f32 v[126:127], v[58:59], v[58:59], v[132:133] op_sel_hi:[1,1,0]
	v_pk_fma_f32 v[132:133], v[46:47], v[46:47], v[162:163] op_sel_hi:[1,1,0]
	v_pk_fma_f32 v[156:157], v[48:49], v[48:49], v[176:177] op_sel_hi:[1,1,0]
	v_mul_f32_e32 v100, v33, v33
	v_mov_b32_e32 v113, v97
	v_pk_add_f32 v[96:97], v[102:103], v[104:105]
	v_pk_add_f32 v[102:103], v[108:109], v[108:109] op_sel_hi:[0,1]
	v_pk_add_f32 v[98:99], v[98:99], v[106:107]
	v_pk_add_f32 v[104:105], v[116:117], v[116:117] op_sel_hi:[0,1]
	v_pk_add_f32 v[106:107], v[118:119], v[120:121]
	v_pk_add_f32 v[94:95], v[94:95], v[94:95] op_sel_hi:[0,1]
	v_pk_add_f32 v[108:109], v[128:129], v[130:131]
	v_mul_f32_e32 v122, v42, v42
	v_mul_f32_e32 v134, v28, v28
	v_mul_f32_e32 v178, v24, v24
	v_mul_f32_e32 v110, v44, v44
	v_mul_f32_e32 v114, v45, v45
	v_mul_f32_e32 v124, v30, v30
	v_mul_f32_e32 v126, v31, v31
	v_mul_f32_e32 v132, v26, v26
	v_mul_f32_e32 v156, v27, v27
	v_pk_add_f32 v[100:101], v[112:113], v[100:101]
	v_mul_f32_e32 v102, v43, v43
	v_mov_b32_e32 v123, v99
	v_mul_f32_e32 v104, v29, v29
	v_mov_b32_e32 v135, v107
	v_mul_f32_e32 v94, v25, v25
	v_mov_b32_e32 v179, v109
	v_pk_add_f32 v[98:99], v[110:111], v[114:115]
	v_pk_add_f32 v[106:107], v[124:125], v[126:127]
	v_pk_add_f32 v[108:109], v[132:133], v[156:157]
	v_pk_add_f32 v[96:97], v[100:101], v[96:97]
	v_pk_add_f32 v[100:101], v[122:123], v[102:103]
	v_pk_add_f32 v[102:103], v[134:135], v[104:105]
	v_pk_add_f32 v[94:95], v[178:179], v[94:95]
	v_add_f32_e32 v91, v96, v97
	v_pk_add_f32 v[96:97], v[100:101], v[98:99]
	v_pk_add_f32 v[98:99], v[102:103], v[106:107]
	v_pk_add_f32 v[94:95], v[94:95], v[108:109]
	v_add_f32_e32 v96, v96, v97
	v_add_f32_e32 v97, v98, v99
	v_add_f32_e32 v94, v94, v95
	ds_bpermute_b32 v95, v84, v91
	ds_bpermute_b32 v98, v84, v96
	ds_bpermute_b32 v99, v84, v97
	ds_bpermute_b32 v100, v84, v94
	s_waitcnt lgkmcnt(3)
	v_add_f32_e32 v91, v91, v95
	s_waitcnt lgkmcnt(2)
	v_add_f32_e32 v95, v96, v98
	s_waitcnt lgkmcnt(1)
	v_add_f32_e32 v96, v97, v99
	ds_bpermute_b32 v97, v85, v91
	s_waitcnt lgkmcnt(1)
	v_add_f32_e32 v94, v94, v100
	ds_bpermute_b32 v98, v85, v95
	ds_bpermute_b32 v99, v85, v96
	ds_bpermute_b32 v100, v85, v94
	s_waitcnt lgkmcnt(3)
	v_add_f32_e32 v91, v91, v97
	ds_bpermute_b32 v97, v86, v91
	s_waitcnt lgkmcnt(3)
	v_add_f32_e32 v95, v95, v98
	s_waitcnt lgkmcnt(2)
	v_add_f32_e32 v96, v96, v99
	s_waitcnt lgkmcnt(1)
	v_add_f32_e32 v94, v94, v100
	ds_bpermute_b32 v98, v86, v95
	ds_bpermute_b32 v99, v86, v96
	ds_bpermute_b32 v100, v86, v94
	s_waitcnt lgkmcnt(3)
	v_add_f32_e32 v91, v91, v97
	ds_bpermute_b32 v97, v87, v91
	s_waitcnt lgkmcnt(3)
	v_add_f32_e32 v95, v95, v98
	s_waitcnt lgkmcnt(2)
	v_add_f32_e32 v96, v96, v99
	s_waitcnt lgkmcnt(1)
	v_add_f32_e32 v94, v94, v100
	ds_bpermute_b32 v98, v87, v95
	ds_bpermute_b32 v99, v87, v96
	ds_bpermute_b32 v100, v87, v94
	s_waitcnt lgkmcnt(3)
	v_add_f32_e32 v91, v91, v97
	ds_bpermute_b32 v97, v88, v91
	s_waitcnt lgkmcnt(3)
	v_add_f32_e32 v95, v95, v98
	s_waitcnt lgkmcnt(2)
	v_add_f32_e32 v96, v96, v99
	s_waitcnt lgkmcnt(1)
	v_add_f32_e32 v94, v94, v100
	ds_bpermute_b32 v98, v88, v95
	ds_bpermute_b32 v99, v88, v96
	ds_bpermute_b32 v100, v88, v94
	s_waitcnt lgkmcnt(3)
	v_add_f32_e32 v91, v91, v97
	ds_bpermute_b32 v97, v89, v91
	s_waitcnt lgkmcnt(3)
	v_add_f32_e32 v95, v95, v98
	s_waitcnt lgkmcnt(2)
	v_add_f32_e32 v96, v96, v99
	s_waitcnt lgkmcnt(1)
	v_add_f32_e32 v94, v94, v100
	ds_bpermute_b32 v98, v89, v95
	ds_bpermute_b32 v99, v89, v96
	ds_bpermute_b32 v100, v89, v94
	s_waitcnt lgkmcnt(3)
	v_add_f32_e32 v91, v91, v97
	v_fmamk_f32 v91, v91, 0x3a800000, v173
	s_waitcnt lgkmcnt(2)
	v_add_f32_e32 v95, v95, v98
	v_mul_f32_e32 v97, 0x4f800000, v91
	v_cmp_gt_f32_e32 vcc, s77, v91
	s_waitcnt lgkmcnt(1)
	v_add_f32_e32 v96, v96, v99
	s_waitcnt lgkmcnt(0)
	v_add_f32_e32 v94, v94, v100
	v_fmamk_f32 v95, v95, 0x3a800000, v173
	v_cndmask_b32_e32 v91, v91, v97, vcc
	v_fmamk_f32 v96, v96, 0x3a800000, v173
	v_fmamk_f32 v94, v94, 0x3a800000, v173
	v_mul_f32_e32 v97, 0x4f800000, v95
	v_cmp_gt_f32_e64 s[0:1], s77, v95
	v_sqrt_f32_e32 v100, v91
	v_mul_f32_e32 v98, 0x4f800000, v96
	v_cmp_gt_f32_e64 s[6:7], s77, v96
	v_mul_f32_e32 v99, 0x4f800000, v94
	v_cmp_gt_f32_e64 s[8:9], s77, v94
	v_cndmask_b32_e64 v95, v95, v97, s[0:1]
	v_cndmask_b32_e64 v96, v96, v98, s[6:7]
	v_cndmask_b32_e64 v94, v94, v99, s[8:9]
	v_sqrt_f32_e32 v97, v95
	v_sqrt_f32_e32 v98, v96
	v_sqrt_f32_e32 v99, v94
	v_add_u32_e32 v101, -1, v100
	v_add_u32_e32 v102, 1, v100
	v_fma_f32 v103, -v101, v100, v91
	v_fma_f32 v104, -v102, v100, v91
	v_add_u32_e32 v105, -1, v97
	v_cmp_ge_f32_e64 s[10:11], 0, v103
	v_add_u32_e32 v106, 1, v97
	v_add_u32_e32 v107, -1, v98
	v_add_u32_e32 v109, -1, v99
	v_cndmask_b32_e64 v100, v100, v101, s[10:11]
	v_fma_f32 v101, -v105, v97, v95
	v_cmp_lt_f32_e64 s[10:11], 0, v104
	v_add_u32_e32 v108, 1, v98
	v_add_u32_e32 v110, 1, v99
	v_fma_f32 v103, -v106, v97, v95
	v_fma_f32 v111, -v107, v98, v96
	v_fma_f32 v113, -v109, v99, v94
	v_cndmask_b32_e64 v100, v100, v102, s[10:11]
	v_cmp_ge_f32_e64 s[10:11], 0, v101
	v_fma_f32 v112, -v108, v98, v96
	v_fma_f32 v114, -v110, v99, v94
	v_cndmask_b32_e64 v97, v97, v105, s[10:11]
	v_cmp_lt_f32_e64 s[10:11], 0, v103
	v_cmp_ge_f32_e64 s[12:13], 0, v111
	v_cmp_ge_f32_e64 s[14:15], 0, v113
	v_mul_f32_e32 v101, 0x37800000, v100
	v_cndmask_b32_e64 v98, v98, v107, s[12:13]
	v_cmp_lt_f32_e64 s[12:13], 0, v112
	v_cndmask_b32_e64 v99, v99, v109, s[14:15]
	v_cmp_lt_f32_e64 s[14:15], 0, v114
	v_cndmask_b32_e64 v97, v97, v106, s[10:11]
	v_cndmask_b32_e64 v98, v98, v108, s[12:13]
	v_cndmask_b32_e64 v99, v99, v110, s[14:15]
	v_cndmask_b32_e32 v100, v100, v101, vcc
	v_mul_f32_e32 v101, 0x37800000, v97
	v_cmp_class_f32_e32 vcc, v91, v174
	v_mul_f32_e32 v102, 0x37800000, v98
	v_mul_f32_e32 v103, 0x37800000, v99
	v_cndmask_b32_e32 v91, v100, v91, vcc
	v_cndmask_b32_e64 v97, v97, v101, s[0:1]
	v_cmp_class_f32_e32 vcc, v95, v174
	v_cndmask_b32_e64 v98, v98, v102, s[6:7]
	v_cmp_class_f32_e64 s[0:1], v96, v174
	v_cndmask_b32_e64 v99, v99, v103, s[8:9]
	v_cmp_class_f32_e64 s[6:7], v94, v174
	v_div_scale_f32 v100, s[8:9], v91, v91, 1.0
	v_cndmask_b32_e32 v95, v97, v95, vcc
	v_cndmask_b32_e64 v102, v98, v96, s[0:1]
	v_cndmask_b32_e64 v103, v99, v94, s[6:7]
	v_rcp_f32_e32 v94, v100
	v_div_scale_f32 v96, s[0:1], v95, v95, 1.0
	v_div_scale_f32 v98, s[6:7], v102, v102, 1.0
	v_rcp_f32_e32 v106, v96
	v_div_scale_f32 v104, s[10:11], v103, v103, 1.0
	v_rcp_f32_e32 v107, v98
	v_rcp_f32_e32 v108, v104
	v_fma_f32 v109, -v100, v94, 1.0
	v_div_scale_f32 v101, s[8:9], 1.0, v91, 1.0
	v_fmac_f32_e32 v94, v109, v94
	v_fma_f32 v109, -v96, v106, 1.0
	v_div_scale_f32 v97, s[0:1], 1.0, v95, 1.0
	v_fma_f32 v110, -v98, v107, 1.0
	v_mul_f32_e32 v112, v101, v94
	v_fmac_f32_e32 v106, v109, v106
	v_div_scale_f32 v99, s[6:7], 1.0, v102, 1.0
	v_fma_f32 v111, -v104, v108, 1.0
	v_fmac_f32_e32 v107, v110, v107
	v_fma_f32 v109, -v100, v112, v101
	v_mul_f32_e32 v110, v97, v106
	v_div_scale_f32 v105, s[10:11], 1.0, v103, 1.0
	v_fmac_f32_e32 v108, v111, v108
	v_mul_f32_e32 v111, v99, v107
	v_fmac_f32_e32 v112, v109, v94
	v_fma_f32 v109, -v96, v110, v97
	v_mul_f32_e32 v113, v105, v108
	v_fma_f32 v114, -v98, v111, v99
	v_fma_f32 v100, -v100, v112, v101
	v_fmac_f32_e32 v110, v109, v106
	s_mov_b64 vcc, s[8:9]
	v_fma_f32 v115, -v104, v113, v105
	v_fmac_f32_e32 v111, v114, v107
	v_div_fmas_f32 v94, v100, v94, v112
	v_fma_f32 v96, -v96, v110, v97
	s_mov_b64 vcc, s[0:1]
	v_fmac_f32_e32 v113, v115, v108
	v_fma_f32 v101, -v98, v111, v99
	v_div_fixup_f32 v94, v94, v91, 1.0
	v_div_fmas_f32 v91, v96, v106, v110
	s_mov_b64 vcc, s[6:7]
	v_fma_f32 v104, -v104, v113, v105
	v_pk_mul_f32 v[60:61], v[94:95], v[60:61] op_sel_hi:[0,1]
	v_pk_mul_f32 v[62:63], v[94:95], v[62:63] op_sel_hi:[0,1]
	v_pk_mul_f32 v[92:93], v[94:95], v[92:93] op_sel_hi:[0,1]
	v_pk_mul_f32 v[64:65], v[94:95], v[64:65] op_sel_hi:[0,1]
	v_pk_mul_f32 v[96:97], v[94:95], v[70:71] op_sel_hi:[0,1]
	v_pk_mul_f32 v[98:99], v[94:95], v[72:73] op_sel_hi:[0,1]
	v_pk_mul_f32 v[32:33], v[94:95], v[32:33] op_sel_hi:[0,1]
	v_pk_mul_f32 v[36:37], v[94:95], v[36:37] op_sel_hi:[0,1]
	v_div_fixup_f32 v100, v91, v95, 1.0
	v_div_fmas_f32 v91, v101, v107, v111
	s_mov_b64 vcc, s[10:11]
	v_pk_mul_f32 v[62:63], v[6:7], v[62:63]
	v_pk_mul_f32 v[60:61], v[4:5], v[60:61]
	v_pk_mul_f32 v[72:73], v[2:3], v[64:65]
	v_pk_mul_f32 v[70:71], v[0:1], v[92:93]
	v_pk_mul_f32 v[94:95], v[14:15], v[98:99]
	v_pk_mul_f32 v[92:93], v[12:13], v[96:97]
	v_pk_mul_f32 v[98:99], v[10:11], v[36:37]
	v_pk_mul_f32 v[96:97], v[8:9], v[32:33]
	v_pk_mul_f32 v[32:33], v[100:101], v[66:67] op_sel_hi:[0,1]
	v_pk_mul_f32 v[36:37], v[100:101], v[68:69] op_sel_hi:[0,1]
	v_pk_mul_f32 v[64:65], v[100:101], v[180:181] op_sel_hi:[0,1]
	v_pk_mul_f32 v[66:67], v[100:101], v[74:75] op_sel_hi:[0,1]
	v_pk_mul_f32 v[68:69], v[100:101], v[76:77] op_sel_hi:[0,1]
	v_pk_mul_f32 v[74:75], v[100:101], v[78:79] op_sel_hi:[0,1]
	v_pk_mul_f32 v[76:77], v[100:101], v[42:43] op_sel_hi:[0,1]
	v_pk_mul_f32 v[78:79], v[100:101], v[44:45] op_sel_hi:[0,1]
	v_div_fixup_f32 v100, v91, v102, 1.0
	v_div_fmas_f32 v91, v104, v108, v113
	global_store_dwordx4 v[22:23], v[60:63], off nt
	global_store_dwordx4 v[22:23], v[70:73], off offset:16 nt
	global_store_dwordx4 v[22:23], v[92:95], off offset:2048 nt
	global_store_dwordx4 v[22:23], v[96:99], off offset:2064 nt
	v_pk_mul_f32 v[44:45], v[6:7], v[36:37]
	v_pk_mul_f32 v[42:43], v[4:5], v[32:33]
	v_pk_mul_f32 v[32:33], v[100:101], v[50:51] op_sel_hi:[0,1]
	v_pk_mul_f32 v[22:23], v[100:101], v[52:53] op_sel_hi:[0,1]
	v_div_fixup_f32 v72, v91, v103, 1.0
	v_pk_mul_f32 v[62:63], v[2:3], v[66:67]
	v_pk_mul_f32 v[60:61], v[0:1], v[64:65]
	v_pk_mul_f32 v[66:67], v[14:15], v[74:75]
	v_pk_mul_f32 v[64:65], v[12:13], v[68:69]
	v_pk_mul_f32 v[70:71], v[10:11], v[78:79]
	v_pk_mul_f32 v[68:69], v[8:9], v[76:77]
	v_pk_mul_f32 v[36:37], v[100:101], v[82:83] op_sel_hi:[0,1]
	v_pk_mul_f32 v[50:51], v[100:101], v[54:55] op_sel_hi:[0,1]
	v_pk_mul_f32 v[52:53], v[100:101], v[56:57] op_sel_hi:[0,1]
	v_pk_mul_f32 v[54:55], v[100:101], v[58:59] op_sel_hi:[0,1]
	v_pk_mul_f32 v[56:57], v[100:101], v[28:29] op_sel_hi:[0,1]
	v_pk_mul_f32 v[58:59], v[100:101], v[30:31] op_sel_hi:[0,1]
	global_store_dwordx4 v[20:21], v[42:45], off nt
	global_store_dwordx4 v[20:21], v[60:63], off offset:16 nt
	global_store_dwordx4 v[20:21], v[64:67], off offset:2048 nt
	global_store_dwordx4 v[20:21], v[68:71], off offset:2064 nt
	v_pk_mul_f32 v[22:23], v[6:7], v[22:23]
	v_pk_mul_f32 v[20:21], v[4:5], v[32:33]
	v_pk_mul_f32 v[32:33], v[72:73], v[34:35] op_sel_hi:[0,1]
	v_pk_mul_f32 v[34:35], v[72:73], v[38:39] op_sel_hi:[0,1]
	s_and_b64 vcc, exec, s[4:5]
	v_pk_mul_f32 v[30:31], v[2:3], v[50:51]
	v_pk_mul_f32 v[28:29], v[0:1], v[36:37]
	v_pk_mul_f32 v[44:45], v[14:15], v[54:55]
	v_pk_mul_f32 v[42:43], v[12:13], v[52:53]
	v_pk_mul_f32 v[52:53], v[10:11], v[58:59]
	v_pk_mul_f32 v[50:51], v[8:9], v[56:57]
	v_pk_mul_f32 v[36:37], v[72:73], v[80:81] op_sel_hi:[0,1]
	v_pk_mul_f32 v[38:39], v[72:73], v[40:41] op_sel_hi:[0,1]
	v_pk_mul_f32 v[40:41], v[72:73], v[46:47] op_sel_hi:[0,1]
	v_pk_mul_f32 v[46:47], v[72:73], v[48:49] op_sel_hi:[0,1]
	v_pk_mul_f32 v[48:49], v[72:73], v[24:25] op_sel_hi:[0,1]
	v_pk_mul_f32 v[54:55], v[72:73], v[26:27] op_sel_hi:[0,1]
	global_store_dwordx4 v[18:19], v[20:23], off nt
	global_store_dwordx4 v[18:19], v[28:31], off offset:16 nt
	global_store_dwordx4 v[18:19], v[42:45], off offset:2048 nt
	global_store_dwordx4 v[18:19], v[50:53], off offset:2064 nt
	v_pk_mul_f32 v[20:21], v[6:7], v[34:35]
	v_pk_mul_f32 v[18:19], v[4:5], v[32:33]
	v_pk_mul_f32 v[24:25], v[2:3], v[38:39]
	v_pk_mul_f32 v[22:23], v[0:1], v[36:37]
	v_pk_mul_f32 v[28:29], v[14:15], v[46:47]
	v_pk_mul_f32 v[26:27], v[12:13], v[40:41]
	v_pk_mul_f32 v[32:33], v[10:11], v[54:55]
	v_pk_mul_f32 v[30:31], v[8:9], v[48:49]
	global_store_dwordx4 v[16:17], v[18:21], off nt
	global_store_dwordx4 v[16:17], v[22:25], off offset:16 nt
	global_store_dwordx4 v[16:17], v[26:29], off offset:2048 nt
	global_store_dwordx4 v[16:17], v[30:33], off offset:2064 nt
	s_cbranch_vccz .LBB0_1005

.LBB0_1036:
	v_or_b32_e32 v24, s19, v17
	v_ashrrev_i32_e32 v25, 31, v24
	v_or_b32_e32 v26, 1, v24
	v_or_b32_e32 v28, 2, v24
	v_or_b32_e32 v32, 3, v24
	v_lshlrev_b64 v[30:31], 11, v[24:25]
	v_ashrrev_i32_e32 v27, 31, v26
	v_ashrrev_i32_e32 v29, 31, v28
	v_ashrrev_i32_e32 v33, 31, v32
	v_lshl_add_u64 v[40:41], v[20:21], 0, v[30:31]
	v_lshlrev_b64 v[42:43], 11, v[26:27]
	v_lshlrev_b64 v[44:45], 11, v[28:29]
	v_lshlrev_b64 v[46:47], 11, v[32:33]
	v_lshlrev_b64 v[48:49], 12, v[32:33]
	global_load_dwordx4 v[32:35], v[40:41], off offset:1024
	global_load_dwordx4 v[36:39], v[40:41], off
	v_lshl_add_u64 v[40:41], v[20:21], 0, v[42:43]
	v_lshl_add_u64 v[42:43], v[20:21], 0, v[44:45]
	v_lshl_add_u64 v[50:51], v[20:21], 0, v[46:47]
	global_load_dwordx4 v[44:47], v[40:41], off offset:1024
	global_load_dwordx4 v[54:57], v[40:41], off
	global_load_dwordx4 v[88:91], v[42:43], off offset:1024
	global_load_dwordx4 v[60:63], v[42:43], off
	global_load_dwordx4 v[100:103], v[50:51], off offset:1024
	global_load_dwordx4 v[104:107], v[50:51], off
	v_lshlrev_b64 v[24:25], 12, v[24:25]
	v_lshl_add_u64 v[30:31], v[22:23], 0, v[24:25]
	v_lshlrev_b64 v[24:25], 12, v[26:27]
	v_lshlrev_b64 v[26:27], 12, v[28:29]
	v_lshl_add_u64 v[28:29], v[22:23], 0, v[24:25]
	v_lshl_add_u64 v[24:25], v[22:23], 0, v[48:49]
	s_and_b64 s[2:3], exec, s[16:17]
	v_lshl_add_u64 v[26:27], v[22:23], 0, v[26:27]
	s_mov_b64 s[16:17], 0
	s_mov_b32 s19, 4
	s_waitcnt vmcnt(5)
	v_lshlrev_b32_e32 v48, 16, v46
	v_lshlrev_b32_e32 v66, 16, v36
	v_lshlrev_b32_e32 v70, 16, v37
	v_and_b32_e32 v73, 0xffff0000, v39
	v_and_b32_e32 v72, 0xffff0000, v38
	v_lshlrev_b32_e32 v78, 16, v32
	v_lshlrev_b32_e32 v80, 16, v33
	v_and_b32_e32 v67, 0xffff0000, v36
	v_and_b32_e32 v71, 0xffff0000, v37
	v_lshlrev_b32_e32 v109, 16, v39
	v_lshlrev_b32_e32 v108, 16, v38
	v_and_b32_e32 v79, 0xffff0000, v32
	v_and_b32_e32 v81, 0xffff0000, v33
	v_mul_f32_e32 v110, v66, v66
	v_mul_f32_e32 v112, v70, v70
	v_pk_mul_f32 v[114:115], v[72:73], v[72:73]
	v_mul_f32_e32 v116, v78, v78
	v_mul_f32_e32 v118, v80, v80
	v_and_b32_e32 v49, 0xffff0000, v46
	s_waitcnt vmcnt(4)
	v_lshlrev_b32_e32 v74, 16, v54
	v_lshlrev_b32_e32 v76, 16, v55
	v_and_b32_e32 v83, 0xffff0000, v57
	v_and_b32_e32 v82, 0xffff0000, v56
	v_lshlrev_b32_e32 v84, 16, v44
	v_and_b32_e32 v85, 0xffff0000, v44
	s_waitcnt vmcnt(2)
	v_lshlrev_b32_e32 v58, 16, v60
	v_lshlrev_b32_e32 v125, 16, v63
	v_lshlrev_b32_e32 v124, 16, v62
	v_and_b32_e32 v63, 0xffff0000, v63
	v_and_b32_e32 v62, 0xffff0000, v62
	v_lshlrev_b32_e32 v64, 16, v88
	s_waitcnt vmcnt(0)
	v_lshlrev_b32_e32 v44, 16, v104
	v_lshlrev_b32_e32 v46, 16, v105
	v_and_b32_e32 v51, 0xffff0000, v107
	v_and_b32_e32 v50, 0xffff0000, v106
	v_lshlrev_b32_e32 v40, 16, v34
	v_and_b32_e32 v41, 0xffff0000, v34
	v_lshlrev_b32_e32 v42, 16, v35
	v_and_b32_e32 v43, 0xffff0000, v35
	v_lshlrev_b32_e32 v52, 16, v47
	v_and_b32_e32 v53, 0xffff0000, v47
	v_and_b32_e32 v75, 0xffff0000, v54
	v_and_b32_e32 v77, 0xffff0000, v55
	v_lshlrev_b32_e32 v123, 16, v57
	v_lshlrev_b32_e32 v122, 16, v56
	v_lshlrev_b32_e32 v86, 16, v45
	v_and_b32_e32 v87, 0xffff0000, v45
	v_and_b32_e32 v59, 0xffff0000, v60
	v_lshlrev_b32_e32 v60, 16, v61
	v_and_b32_e32 v65, 0xffff0000, v88
	v_lshlrev_b32_e32 v68, 16, v89
	v_lshlrev_b32_e32 v32, 16, v102
	v_and_b32_e32 v33, 0xffff0000, v102
	v_lshlrev_b32_e32 v34, 16, v103
	v_and_b32_e32 v35, 0xffff0000, v103
	v_and_b32_e32 v45, 0xffff0000, v104
	v_and_b32_e32 v47, 0xffff0000, v105
	v_lshlrev_b32_e32 v103, 16, v107
	v_lshlrev_b32_e32 v102, 16, v106
	v_lshlrev_b32_e32 v54, 16, v100
	v_and_b32_e32 v55, 0xffff0000, v100
	v_lshlrev_b32_e32 v56, 16, v101
	v_and_b32_e32 v57, 0xffff0000, v101
	v_mov_b32_e32 v100, v108
	v_mov_b32_e32 v101, v72
	v_mov_b32_e32 v72, v109
	v_pk_fma_f32 v[104:105], v[66:67], v[66:67], v[110:111] op_sel_hi:[1,1,0]
	v_pk_fma_f32 v[106:107], v[70:71], v[70:71], v[112:113] op_sel_hi:[1,1,0]
	v_pk_fma_f32 v[108:109], v[108:109], v[108:109], v[114:115]
	v_pk_fma_f32 v[110:111], v[78:79], v[78:79], v[116:117] op_sel_hi:[1,1,0]
	v_pk_fma_f32 v[112:113], v[80:81], v[80:81], v[118:119] op_sel_hi:[1,1,0]
	v_mul_f32_e32 v114, v74, v74
	v_mul_f32_e32 v116, v76, v76
	v_pk_mul_f32 v[118:119], v[82:83], v[82:83]
	v_mul_f32_e32 v126, v84, v84
	v_mul_f32_e32 v132, v58, v58
	v_pk_mul_f32 v[136:137], v[62:63], v[62:63]
	v_mul_f32_e32 v138, v64, v64
	v_mul_f32_e32 v144, v44, v44
	v_mul_f32_e32 v146, v46, v46
	v_pk_mul_f32 v[148:149], v[50:51], v[50:51]
	v_lshlrev_b32_e32 v36, 16, v90
	v_and_b32_e32 v37, 0xffff0000, v90
	v_lshlrev_b32_e32 v38, 16, v91
	v_and_b32_e32 v39, 0xffff0000, v91
	v_and_b32_e32 v61, 0xffff0000, v61
	v_and_b32_e32 v69, 0xffff0000, v89
	v_mul_f32_e32 v128, v86, v86
	v_mul_f32_e32 v134, v60, v60
	v_mul_f32_e32 v140, v68, v68
	v_mul_f32_e32 v150, v54, v54
	v_mul_f32_e32 v152, v56, v56
	v_mov_b32_e32 v90, v124
	v_mov_b32_e32 v91, v62
	v_mov_b32_e32 v62, v125
	v_mov_b32_e32 v88, v102
	v_mov_b32_e32 v89, v50
	v_mov_b32_e32 v50, v103
	v_pk_add_f32 v[108:109], v[108:109], v[108:109] op_sel_hi:[0,1]
	v_mul_f32_e32 v110, v42, v42
	v_mul_f32_e32 v112, v43, v43
	v_pk_add_f32 v[104:105], v[104:105], v[106:107]
	v_pk_fma_f32 v[106:107], v[74:75], v[74:75], v[114:115] op_sel_hi:[1,1,0]
	v_pk_fma_f32 v[114:115], v[76:77], v[76:77], v[116:117] op_sel_hi:[1,1,0]
	v_pk_fma_f32 v[116:117], v[122:123], v[122:123], v[118:119]
	v_pk_fma_f32 v[118:119], v[84:85], v[84:85], v[126:127] op_sel_hi:[1,1,0]
	v_pk_fma_f32 v[126:127], v[58:59], v[58:59], v[132:133] op_sel_hi:[1,1,0]
	v_pk_fma_f32 v[124:125], v[124:125], v[124:125], v[136:137]
	v_pk_fma_f32 v[132:133], v[64:65], v[64:65], v[138:139] op_sel_hi:[1,1,0]
	v_pk_fma_f32 v[136:137], v[44:45], v[44:45], v[144:145] op_sel_hi:[1,1,0]
	v_pk_fma_f32 v[138:139], v[46:47], v[46:47], v[146:147] op_sel_hi:[1,1,0]
	v_pk_fma_f32 v[102:103], v[102:103], v[102:103], v[148:149]
	v_mul_f32_e32 v120, v40, v40
	v_mov_b32_e32 v156, v122
	v_mov_b32_e32 v157, v82
	v_mov_b32_e32 v82, v123
	v_pk_fma_f32 v[122:123], v[86:87], v[86:87], v[128:129] op_sel_hi:[1,1,0]
	v_pk_fma_f32 v[128:129], v[60:61], v[60:61], v[134:135] op_sel_hi:[1,1,0]
	v_pk_fma_f32 v[134:135], v[68:69], v[68:69], v[140:141] op_sel_hi:[1,1,0]
	v_pk_fma_f32 v[140:141], v[54:55], v[54:55], v[150:151] op_sel_hi:[1,1,0]
	v_pk_fma_f32 v[144:145], v[56:57], v[56:57], v[152:153] op_sel_hi:[1,1,0]
	v_mul_f32_e32 v108, v41, v41
	v_mov_b32_e32 v121, v105
	v_pk_add_f32 v[104:105], v[110:111], v[112:113]
	v_pk_add_f32 v[110:111], v[116:117], v[116:117] op_sel_hi:[0,1]
	v_pk_add_f32 v[106:107], v[106:107], v[114:115]
	v_pk_add_f32 v[102:103], v[102:103], v[102:103] op_sel_hi:[0,1]
	v_pk_add_f32 v[116:117], v[136:137], v[138:139]
	v_mul_f32_e32 v130, v48, v48
	v_mul_f32_e32 v154, v32, v32
	v_mul_f32_e32 v118, v52, v52
	v_mul_f32_e32 v122, v53, v53
	v_pk_add_f32 v[112:113], v[124:125], v[124:125] op_sel_hi:[0,1]
	v_pk_add_f32 v[114:115], v[126:127], v[128:129]
	v_mul_f32_e32 v140, v34, v34
	v_mul_f32_e32 v144, v35, v35
	v_pk_add_f32 v[108:109], v[120:121], v[108:109]
	v_mul_f32_e32 v110, v49, v49
	v_mov_b32_e32 v131, v107
	v_mul_f32_e32 v102, v33, v33
	v_mov_b32_e32 v155, v117
	v_mul_f32_e32 v142, v36, v36
	v_mul_f32_e32 v132, v38, v38
	v_mul_f32_e32 v134, v39, v39
	v_pk_add_f32 v[106:107], v[118:119], v[122:123]
	v_mul_f32_e32 v112, v37, v37
	v_mov_b32_e32 v143, v115
	v_pk_add_f32 v[116:117], v[140:141], v[144:145]
	v_pk_add_f32 v[104:105], v[108:109], v[104:105]
	v_pk_add_f32 v[108:109], v[130:131], v[110:111]
	v_pk_add_f32 v[102:103], v[154:155], v[102:103]
	v_pk_add_f32 v[114:115], v[132:133], v[134:135]
	v_pk_add_f32 v[110:111], v[142:143], v[112:113]
	v_add_f32_e32 v112, v104, v105
	v_pk_add_f32 v[104:105], v[108:109], v[106:107]
	v_pk_add_f32 v[102:103], v[102:103], v[116:117]
	v_pk_add_f32 v[106:107], v[110:111], v[114:115]
	v_add_f32_e32 v104, v104, v105
	v_add_f32_e32 v102, v102, v103
	ds_bpermute_b32 v103, v93, v112
	v_add_f32_e32 v105, v106, v107
	ds_bpermute_b32 v106, v93, v104
	ds_bpermute_b32 v107, v93, v105
	ds_bpermute_b32 v108, v93, v102
	s_waitcnt lgkmcnt(3)
	v_add_f32_e32 v103, v112, v103
	s_waitcnt lgkmcnt(2)
	v_add_f32_e32 v104, v104, v106
	ds_bpermute_b32 v106, v94, v103
	s_waitcnt lgkmcnt(2)
	v_add_f32_e32 v105, v105, v107
	s_waitcnt lgkmcnt(1)
	v_add_f32_e32 v102, v102, v108
	ds_bpermute_b32 v107, v94, v104
	ds_bpermute_b32 v108, v94, v105
	ds_bpermute_b32 v109, v94, v102
	s_waitcnt lgkmcnt(3)
	v_add_f32_e32 v103, v103, v106
	ds_bpermute_b32 v106, v95, v103
	s_waitcnt lgkmcnt(3)
	v_add_f32_e32 v104, v104, v107
	s_waitcnt lgkmcnt(2)
	v_add_f32_e32 v105, v105, v108
	s_waitcnt lgkmcnt(1)
	v_add_f32_e32 v102, v102, v109
	ds_bpermute_b32 v107, v95, v104
	ds_bpermute_b32 v108, v95, v105
	ds_bpermute_b32 v109, v95, v102
	s_waitcnt lgkmcnt(3)
	v_add_f32_e32 v103, v103, v106
	ds_bpermute_b32 v106, v96, v103
	s_waitcnt lgkmcnt(3)
	v_add_f32_e32 v104, v104, v107
	s_waitcnt lgkmcnt(2)
	v_add_f32_e32 v105, v105, v108
	s_waitcnt lgkmcnt(1)
	v_add_f32_e32 v102, v102, v109
	ds_bpermute_b32 v107, v96, v104
	ds_bpermute_b32 v108, v96, v105
	ds_bpermute_b32 v109, v96, v102
	s_waitcnt lgkmcnt(3)
	v_add_f32_e32 v103, v103, v106
	ds_bpermute_b32 v106, v97, v103
	s_waitcnt lgkmcnt(3)
	v_add_f32_e32 v104, v104, v107
	s_waitcnt lgkmcnt(2)
	v_add_f32_e32 v105, v105, v108
	s_waitcnt lgkmcnt(1)
	v_add_f32_e32 v102, v102, v109
	ds_bpermute_b32 v107, v97, v104
	ds_bpermute_b32 v108, v97, v105
	ds_bpermute_b32 v109, v97, v102
	s_waitcnt lgkmcnt(3)
	v_add_f32_e32 v103, v103, v106
	ds_bpermute_b32 v106, v98, v103
	s_waitcnt lgkmcnt(3)
	v_add_f32_e32 v104, v104, v107
	s_waitcnt lgkmcnt(2)
	v_add_f32_e32 v105, v105, v108
	s_waitcnt lgkmcnt(1)
	v_add_f32_e32 v102, v102, v109
	ds_bpermute_b32 v107, v98, v104
	ds_bpermute_b32 v108, v98, v105
	ds_bpermute_b32 v109, v98, v102
	s_waitcnt lgkmcnt(3)
	v_add_f32_e32 v103, v103, v106
	v_fmamk_f32 v103, v103, 0x3a800000, v19
	s_waitcnt lgkmcnt(2)
	v_add_f32_e32 v104, v104, v107
	v_mul_f32_e32 v106, 0x4f800000, v103
	v_cmp_gt_f32_e32 vcc, s15, v103
	s_waitcnt lgkmcnt(1)
	v_add_f32_e32 v105, v105, v108
	s_waitcnt lgkmcnt(0)
	v_add_f32_e32 v102, v102, v109
	v_fmamk_f32 v104, v104, 0x3a800000, v19
	v_cndmask_b32_e32 v103, v103, v106, vcc
	v_fmamk_f32 v105, v105, 0x3a800000, v19
	v_fmamk_f32 v102, v102, 0x3a800000, v19
	v_mul_f32_e32 v106, 0x4f800000, v104
	v_cmp_gt_f32_e64 s[0:1], s15, v104
	v_sqrt_f32_e32 v109, v103
	v_mul_f32_e32 v107, 0x4f800000, v105
	v_cmp_gt_f32_e64 s[4:5], s15, v105
	v_mul_f32_e32 v108, 0x4f800000, v102
	v_cmp_gt_f32_e64 s[6:7], s15, v102
	v_cndmask_b32_e64 v104, v104, v106, s[0:1]
	v_cndmask_b32_e64 v105, v105, v107, s[4:5]
	v_cndmask_b32_e64 v102, v102, v108, s[6:7]
	v_sqrt_f32_e32 v106, v104
	v_sqrt_f32_e32 v107, v105
	v_sqrt_f32_e32 v108, v102
	v_add_u32_e32 v110, -1, v109
	v_add_u32_e32 v111, 1, v109
	v_fma_f32 v112, -v110, v109, v103
	v_fma_f32 v113, -v111, v109, v103
	v_add_u32_e32 v114, -1, v106
	v_cmp_ge_f32_e64 s[8:9], 0, v112
	v_add_u32_e32 v115, 1, v106
	v_add_u32_e32 v116, -1, v107
	v_add_u32_e32 v118, -1, v108
	v_cndmask_b32_e64 v109, v109, v110, s[8:9]
	v_fma_f32 v110, -v114, v106, v104
	v_cmp_lt_f32_e64 s[8:9], 0, v113
	v_add_u32_e32 v117, 1, v107
	v_add_u32_e32 v119, 1, v108
	v_fma_f32 v112, -v115, v106, v104
	v_fma_f32 v120, -v116, v107, v105
	v_fma_f32 v122, -v118, v108, v102
	v_cndmask_b32_e64 v109, v109, v111, s[8:9]
	v_cmp_ge_f32_e64 s[8:9], 0, v110
	v_fma_f32 v121, -v117, v107, v105
	v_fma_f32 v123, -v119, v108, v102
	v_cndmask_b32_e64 v106, v106, v114, s[8:9]
	v_cmp_lt_f32_e64 s[8:9], 0, v112
	v_cmp_ge_f32_e64 s[10:11], 0, v120
	v_cmp_ge_f32_e64 s[12:13], 0, v122
	v_mul_f32_e32 v110, 0x37800000, v109
	v_cndmask_b32_e64 v107, v107, v116, s[10:11]
	v_cmp_lt_f32_e64 s[10:11], 0, v121
	v_cndmask_b32_e64 v108, v108, v118, s[12:13]
	v_cmp_lt_f32_e64 s[12:13], 0, v123
	v_cndmask_b32_e64 v106, v106, v115, s[8:9]
	v_cndmask_b32_e64 v107, v107, v117, s[10:11]
	v_cndmask_b32_e64 v108, v108, v119, s[12:13]
	v_cndmask_b32_e32 v109, v109, v110, vcc
	v_mul_f32_e32 v110, 0x37800000, v106
	v_cmp_class_f32_e32 vcc, v103, v99
	v_mul_f32_e32 v111, 0x37800000, v107
	v_mul_f32_e32 v112, 0x37800000, v108
	v_cndmask_b32_e32 v103, v109, v103, vcc
	v_cndmask_b32_e64 v106, v106, v110, s[0:1]
	v_cmp_class_f32_e32 vcc, v104, v99
	v_cndmask_b32_e64 v107, v107, v111, s[4:5]
	v_cmp_class_f32_e64 s[0:1], v105, v99
	v_cndmask_b32_e64 v108, v108, v112, s[6:7]
	v_cmp_class_f32_e64 s[4:5], v102, v99
	v_div_scale_f32 v109, s[6:7], v103, v103, 1.0
	v_cndmask_b32_e32 v106, v106, v104, vcc
	v_cndmask_b32_e64 v107, v107, v105, s[0:1]
	v_cndmask_b32_e64 v108, v108, v102, s[4:5]
	v_rcp_f32_e32 v102, v109
	v_div_scale_f32 v104, s[0:1], v106, v106, 1.0
	v_div_scale_f32 v111, s[4:5], v107, v107, 1.0
	v_rcp_f32_e32 v115, v104
	v_div_scale_f32 v113, s[8:9], v108, v108, 1.0
	v_rcp_f32_e32 v116, v111
	v_rcp_f32_e32 v117, v113
	v_fma_f32 v118, -v109, v102, 1.0
	v_div_scale_f32 v110, s[6:7], 1.0, v103, 1.0
	v_fmac_f32_e32 v102, v118, v102
	v_fma_f32 v118, -v104, v115, 1.0
	v_div_scale_f32 v105, s[0:1], 1.0, v106, 1.0
	v_fma_f32 v119, -v111, v116, 1.0
	v_mul_f32_e32 v121, v110, v102
	v_fmac_f32_e32 v115, v118, v115
	v_div_scale_f32 v112, s[4:5], 1.0, v107, 1.0
	v_fma_f32 v120, -v113, v117, 1.0
	v_fmac_f32_e32 v116, v119, v116
	v_fma_f32 v118, -v109, v121, v110
	v_mul_f32_e32 v119, v105, v115
	v_div_scale_f32 v114, s[8:9], 1.0, v108, 1.0
	v_fmac_f32_e32 v117, v120, v117
	v_mul_f32_e32 v120, v112, v116
	v_fmac_f32_e32 v121, v118, v102
	v_fma_f32 v118, -v104, v119, v105
	v_mul_f32_e32 v122, v114, v117
	v_fma_f32 v123, -v111, v120, v112
	v_fma_f32 v109, -v109, v121, v110
	v_fmac_f32_e32 v119, v118, v115
	s_mov_b64 vcc, s[6:7]
	v_fma_f32 v124, -v113, v122, v114
	v_fmac_f32_e32 v120, v123, v116
	v_div_fmas_f32 v102, v109, v102, v121
	v_fma_f32 v104, -v104, v119, v105
	s_mov_b64 vcc, s[0:1]
	v_fmac_f32_e32 v122, v124, v117
	v_fma_f32 v109, -v111, v120, v112
	v_div_fixup_f32 v102, v102, v103, 1.0
	v_div_fmas_f32 v111, v104, v115, v119
	s_mov_b64 vcc, s[4:5]
	v_fma_f32 v110, -v113, v122, v114
	v_pk_mul_f32 v[66:67], v[102:103], v[66:67] op_sel_hi:[0,1]
	v_pk_mul_f32 v[70:71], v[102:103], v[70:71] op_sel_hi:[0,1]
	v_pk_mul_f32 v[100:101], v[102:103], v[100:101] op_sel_hi:[0,1]
	v_pk_mul_f32 v[78:79], v[102:103], v[78:79] op_sel_hi:[0,1]
	v_pk_mul_f32 v[104:105], v[102:103], v[40:41] op_sel_hi:[0,1]
	v_div_fixup_f32 v106, v111, v106, 1.0
	v_div_fmas_f32 v109, v109, v116, v120
	s_mov_b64 vcc, s[8:9]
	v_pk_mul_f32 v[72:73], v[102:103], v[72:73] op_sel_hi:[0,1]
	v_pk_mul_f32 v[80:81], v[102:103], v[80:81] op_sel_hi:[0,1]
	v_pk_mul_f32 v[102:103], v[102:103], v[42:43] op_sel_hi:[0,1]
	v_pk_mul_f32 v[42:43], v[6:7], v[70:71]
	v_pk_mul_f32 v[40:41], v[4:5], v[66:67]
	v_pk_mul_f32 v[70:71], v[0:1], v[100:101]
	v_pk_mul_f32 v[78:79], v[12:13], v[78:79]
	v_pk_mul_f32 v[100:101], v[8:9], v[104:105]
	v_pk_mul_f32 v[66:67], v[106:107], v[74:75] op_sel_hi:[0,1]
	v_pk_mul_f32 v[74:75], v[106:107], v[76:77] op_sel_hi:[0,1]
	v_pk_mul_f32 v[48:49], v[106:107], v[48:49] op_sel_hi:[0,1]
	v_div_fixup_f32 v104, v109, v107, 1.0
	v_div_fmas_f32 v105, v110, v117, v122
	v_pk_mul_f32 v[72:73], v[2:3], v[72:73]
	v_pk_mul_f32 v[80:81], v[14:15], v[80:81]
	v_pk_mul_f32 v[102:103], v[10:11], v[102:103]
	v_pk_mul_f32 v[76:77], v[106:107], v[156:157] op_sel_hi:[0,1]
	v_pk_mul_f32 v[82:83], v[106:107], v[82:83] op_sel_hi:[0,1]
	v_pk_mul_f32 v[84:85], v[106:107], v[84:85] op_sel_hi:[0,1]
	v_pk_mul_f32 v[86:87], v[106:107], v[86:87] op_sel_hi:[0,1]
	v_pk_mul_f32 v[52:53], v[106:107], v[52:53] op_sel_hi:[0,1]
	global_store_dwordx4 v[30:31], v[40:43], off nt
	global_store_dwordx4 v[30:31], v[70:73], off offset:16 nt
	global_store_dwordx4 v[30:31], v[78:81], off offset:2048 nt
	global_store_dwordx4 v[30:31], v[100:103], off offset:2064 nt
	v_pk_mul_f32 v[42:43], v[6:7], v[74:75]
	v_pk_mul_f32 v[40:41], v[4:5], v[66:67]
	v_pk_mul_f32 v[78:79], v[8:9], v[48:49]
	v_pk_mul_f32 v[48:49], v[104:105], v[58:59] op_sel_hi:[0,1]
	v_pk_mul_f32 v[30:31], v[104:105], v[60:61] op_sel_hi:[0,1]
	v_pk_mul_f32 v[58:59], v[104:105], v[62:63] op_sel_hi:[0,1]
	v_pk_mul_f32 v[62:63], v[104:105], v[68:69] op_sel_hi:[0,1]
	v_div_fixup_f32 v68, v105, v108, 1.0
	v_pk_mul_f32 v[72:73], v[2:3], v[82:83]
	v_pk_mul_f32 v[70:71], v[0:1], v[76:77]
	v_pk_mul_f32 v[76:77], v[14:15], v[86:87]
	v_pk_mul_f32 v[74:75], v[12:13], v[84:85]
	v_pk_mul_f32 v[80:81], v[10:11], v[52:53]
	v_pk_mul_f32 v[52:53], v[104:105], v[90:91] op_sel_hi:[0,1]
	v_pk_mul_f32 v[60:61], v[104:105], v[64:65] op_sel_hi:[0,1]
	v_pk_mul_f32 v[64:65], v[104:105], v[36:37] op_sel_hi:[0,1]
	v_pk_mul_f32 v[66:67], v[104:105], v[38:39] op_sel_hi:[0,1]
	global_store_dwordx4 v[28:29], v[40:43], off nt
	global_store_dwordx4 v[28:29], v[70:73], off offset:16 nt
	global_store_dwordx4 v[28:29], v[74:77], off offset:2048 nt
	global_store_dwordx4 v[28:29], v[78:81], off offset:2064 nt
	v_pk_mul_f32 v[30:31], v[6:7], v[30:31]
	v_pk_mul_f32 v[28:29], v[4:5], v[48:49]
	v_pk_mul_f32 v[44:45], v[68:69], v[44:45] op_sel_hi:[0,1]
	v_pk_mul_f32 v[46:47], v[68:69], v[46:47] op_sel_hi:[0,1]
	v_pk_mul_f32 v[38:39], v[2:3], v[58:59]
	v_pk_mul_f32 v[36:37], v[0:1], v[52:53]
	v_pk_mul_f32 v[42:43], v[14:15], v[62:63]
	v_pk_mul_f32 v[40:41], v[12:13], v[60:61]
	v_pk_mul_f32 v[60:61], v[10:11], v[66:67]
	v_pk_mul_f32 v[58:59], v[8:9], v[64:65]
	v_pk_mul_f32 v[48:49], v[68:69], v[88:89] op_sel_hi:[0,1]
	v_pk_mul_f32 v[50:51], v[68:69], v[50:51] op_sel_hi:[0,1]
	v_pk_mul_f32 v[52:53], v[68:69], v[54:55] op_sel_hi:[0,1]
	v_pk_mul_f32 v[54:55], v[68:69], v[56:57] op_sel_hi:[0,1]
	v_pk_mul_f32 v[56:57], v[68:69], v[32:33] op_sel_hi:[0,1]
	v_pk_mul_f32 v[62:63], v[68:69], v[34:35] op_sel_hi:[0,1]
	global_store_dwordx4 v[26:27], v[28:31], off nt
	global_store_dwordx4 v[26:27], v[36:39], off offset:16 nt
	global_store_dwordx4 v[26:27], v[40:43], off offset:2048 nt
	global_store_dwordx4 v[26:27], v[58:61], off offset:2064 nt
	v_pk_mul_f32 v[28:29], v[6:7], v[46:47]
	v_pk_mul_f32 v[26:27], v[4:5], v[44:45]
	s_mov_b64 vcc, s[2:3]
	v_pk_mul_f32 v[32:33], v[2:3], v[50:51]
	v_pk_mul_f32 v[30:31], v[0:1], v[48:49]
	v_pk_mul_f32 v[36:37], v[14:15], v[54:55]
	v_pk_mul_f32 v[34:35], v[12:13], v[52:53]
	v_pk_mul_f32 v[40:41], v[10:11], v[62:63]
	v_pk_mul_f32 v[38:39], v[8:9], v[56:57]
	global_store_dwordx4 v[24:25], v[26:29], off nt
	global_store_dwordx4 v[24:25], v[30:33], off offset:16 nt
	global_store_dwordx4 v[24:25], v[34:37], off offset:2048 nt
	global_store_dwordx4 v[24:25], v[38:41], off offset:2064 nt
	s_cbranch_vccnz .LBB0_1036

.LBB0_1054:
	v_or_b32_e32 v18, s17, v94
	v_ashrrev_i32_e32 v19, 31, v18
	v_or_b32_e32 v22, 1, v18
	v_or_b32_e32 v24, 2, v18
	v_or_b32_e32 v28, 3, v18
	v_lshlrev_b64 v[26:27], 11, v[18:19]
	v_ashrrev_i32_e32 v23, 31, v22
	v_ashrrev_i32_e32 v25, 31, v24
	v_ashrrev_i32_e32 v29, 31, v28
	v_lshl_add_u64 v[36:37], v[20:21], 0, v[26:27]
	v_lshlrev_b64 v[38:39], 11, v[22:23]
	v_lshlrev_b64 v[40:41], 11, v[24:25]
	v_lshlrev_b64 v[42:43], 11, v[28:29]
	v_lshlrev_b64 v[44:45], 12, v[28:29]
	global_load_dwordx4 v[28:31], v[36:37], off offset:1024
	global_load_dwordx4 v[32:35], v[36:37], off
	v_lshl_add_u64 v[36:37], v[20:21], 0, v[38:39]
	v_lshl_add_u64 v[38:39], v[20:21], 0, v[40:41]
	v_lshl_add_u64 v[46:47], v[20:21], 0, v[42:43]
	global_load_dwordx4 v[40:43], v[36:37], off offset:1024
	global_load_dwordx4 v[50:53], v[36:37], off
	global_load_dwordx4 v[84:87], v[38:39], off offset:1024
	global_load_dwordx4 v[56:59], v[38:39], off
	global_load_dwordx4 v[98:101], v[46:47], off offset:1024
	global_load_dwordx4 v[102:105], v[46:47], off
	v_lshlrev_b64 v[18:19], 12, v[18:19]
	v_lshl_add_u64 v[26:27], v[16:17], 0, v[18:19]
	v_lshlrev_b64 v[18:19], 12, v[22:23]
	v_lshlrev_b64 v[22:23], 12, v[24:25]
	v_lshl_add_u64 v[24:25], v[16:17], 0, v[18:19]
	v_lshl_add_u64 v[18:19], v[16:17], 0, v[44:45]
	s_and_b64 s[0:1], exec, s[14:15]
	v_lshl_add_u64 v[22:23], v[16:17], 0, v[22:23]
	s_mov_b64 s[14:15], 0
	s_mov_b32 s17, 4
	s_waitcnt vmcnt(5)
	v_lshlrev_b32_e32 v44, 16, v42
	v_lshlrev_b32_e32 v62, 16, v32
	v_lshlrev_b32_e32 v66, 16, v33
	v_and_b32_e32 v69, 0xffff0000, v35
	v_and_b32_e32 v68, 0xffff0000, v34
	v_lshlrev_b32_e32 v74, 16, v28
	v_lshlrev_b32_e32 v76, 16, v29
	v_and_b32_e32 v63, 0xffff0000, v32
	v_and_b32_e32 v67, 0xffff0000, v33
	v_lshlrev_b32_e32 v107, 16, v35
	v_lshlrev_b32_e32 v106, 16, v34
	v_and_b32_e32 v75, 0xffff0000, v28
	v_and_b32_e32 v77, 0xffff0000, v29
	v_mul_f32_e32 v108, v62, v62
	v_mul_f32_e32 v110, v66, v66
	v_pk_mul_f32 v[112:113], v[68:69], v[68:69]
	v_mul_f32_e32 v114, v74, v74
	v_mul_f32_e32 v116, v76, v76
	v_and_b32_e32 v45, 0xffff0000, v42
	s_waitcnt vmcnt(4)
	v_lshlrev_b32_e32 v70, 16, v50
	v_lshlrev_b32_e32 v72, 16, v51
	v_and_b32_e32 v79, 0xffff0000, v53
	v_and_b32_e32 v78, 0xffff0000, v52
	v_lshlrev_b32_e32 v80, 16, v40
	v_and_b32_e32 v81, 0xffff0000, v40
	v_lshlrev_b32_e32 v82, 16, v41
	s_waitcnt vmcnt(2)
	v_lshlrev_b32_e32 v54, 16, v56
	v_and_b32_e32 v55, 0xffff0000, v56
	v_lshlrev_b32_e32 v56, 16, v57
	v_lshlrev_b32_e32 v123, 16, v59
	v_lshlrev_b32_e32 v122, 16, v58
	v_and_b32_e32 v59, 0xffff0000, v59
	v_and_b32_e32 v58, 0xffff0000, v58
	v_lshlrev_b32_e32 v60, 16, v84
	s_waitcnt vmcnt(0)
	v_lshlrev_b32_e32 v40, 16, v102
	v_lshlrev_b32_e32 v42, 16, v103
	v_and_b32_e32 v47, 0xffff0000, v105
	v_and_b32_e32 v46, 0xffff0000, v104
	v_lshlrev_b32_e32 v36, 16, v30
	v_and_b32_e32 v37, 0xffff0000, v30
	v_lshlrev_b32_e32 v38, 16, v31
	v_and_b32_e32 v39, 0xffff0000, v31
	v_lshlrev_b32_e32 v48, 16, v43
	v_and_b32_e32 v49, 0xffff0000, v43
	v_and_b32_e32 v71, 0xffff0000, v50
	v_and_b32_e32 v73, 0xffff0000, v51
	v_lshlrev_b32_e32 v121, 16, v53
	v_lshlrev_b32_e32 v120, 16, v52
	v_and_b32_e32 v83, 0xffff0000, v41
	v_and_b32_e32 v57, 0xffff0000, v57
	v_and_b32_e32 v61, 0xffff0000, v84
	v_lshlrev_b32_e32 v64, 16, v85
	v_lshlrev_b32_e32 v28, 16, v100
	v_and_b32_e32 v29, 0xffff0000, v100
	v_lshlrev_b32_e32 v30, 16, v101
	v_and_b32_e32 v31, 0xffff0000, v101
	v_and_b32_e32 v41, 0xffff0000, v102
	v_and_b32_e32 v43, 0xffff0000, v103
	v_lshlrev_b32_e32 v101, 16, v105
	v_lshlrev_b32_e32 v100, 16, v104
	v_lshlrev_b32_e32 v50, 16, v98
	v_and_b32_e32 v51, 0xffff0000, v98
	v_lshlrev_b32_e32 v52, 16, v99
	v_and_b32_e32 v53, 0xffff0000, v99
	v_mov_b32_e32 v98, v106
	v_mov_b32_e32 v99, v68
	v_mov_b32_e32 v68, v107
	v_pk_fma_f32 v[102:103], v[62:63], v[62:63], v[108:109] op_sel_hi:[1,1,0]
	v_pk_fma_f32 v[104:105], v[66:67], v[66:67], v[110:111] op_sel_hi:[1,1,0]
	v_pk_fma_f32 v[106:107], v[106:107], v[106:107], v[112:113]
	v_pk_fma_f32 v[108:109], v[74:75], v[74:75], v[114:115] op_sel_hi:[1,1,0]
	v_pk_fma_f32 v[110:111], v[76:77], v[76:77], v[116:117] op_sel_hi:[1,1,0]
	v_mul_f32_e32 v112, v70, v70
	v_mul_f32_e32 v114, v72, v72
	v_pk_mul_f32 v[116:117], v[78:79], v[78:79]
	v_mul_f32_e32 v124, v80, v80
	v_mul_f32_e32 v126, v82, v82
	v_mul_f32_e32 v130, v54, v54
	v_mul_f32_e32 v132, v56, v56
	v_pk_mul_f32 v[134:135], v[58:59], v[58:59]
	v_mul_f32_e32 v136, v60, v60
	v_mul_f32_e32 v142, v40, v40
	v_mul_f32_e32 v144, v42, v42
	v_pk_mul_f32 v[146:147], v[46:47], v[46:47]
	v_lshlrev_b32_e32 v32, 16, v86
	v_and_b32_e32 v33, 0xffff0000, v86
	v_lshlrev_b32_e32 v34, 16, v87
	v_and_b32_e32 v35, 0xffff0000, v87
	v_and_b32_e32 v65, 0xffff0000, v85
	v_mul_f32_e32 v138, v64, v64
	v_mul_f32_e32 v148, v50, v50
	v_mul_f32_e32 v150, v52, v52
	v_mov_b32_e32 v154, v120
	v_mov_b32_e32 v155, v78
	v_mov_b32_e32 v78, v121
	v_mov_b32_e32 v86, v122
	v_mov_b32_e32 v87, v58
	v_mov_b32_e32 v58, v123
	v_mov_b32_e32 v84, v100
	v_mov_b32_e32 v85, v46
	v_mov_b32_e32 v46, v101
	v_pk_add_f32 v[106:107], v[106:107], v[106:107] op_sel_hi:[0,1]
	v_mul_f32_e32 v108, v38, v38
	v_mul_f32_e32 v110, v39, v39
	v_pk_add_f32 v[102:103], v[102:103], v[104:105]
	v_pk_fma_f32 v[104:105], v[70:71], v[70:71], v[112:113] op_sel_hi:[1,1,0]
	v_pk_fma_f32 v[112:113], v[72:73], v[72:73], v[114:115] op_sel_hi:[1,1,0]
	v_pk_fma_f32 v[114:115], v[120:121], v[120:121], v[116:117]
	v_pk_fma_f32 v[116:117], v[80:81], v[80:81], v[124:125] op_sel_hi:[1,1,0]
	v_pk_fma_f32 v[120:121], v[82:83], v[82:83], v[126:127] op_sel_hi:[1,1,0]
	v_pk_fma_f32 v[124:125], v[54:55], v[54:55], v[130:131] op_sel_hi:[1,1,0]
	v_pk_fma_f32 v[126:127], v[56:57], v[56:57], v[132:133] op_sel_hi:[1,1,0]
	v_pk_fma_f32 v[122:123], v[122:123], v[122:123], v[134:135]
	v_pk_fma_f32 v[130:131], v[60:61], v[60:61], v[136:137] op_sel_hi:[1,1,0]
	v_pk_fma_f32 v[134:135], v[40:41], v[40:41], v[142:143] op_sel_hi:[1,1,0]
	v_pk_fma_f32 v[136:137], v[42:43], v[42:43], v[144:145] op_sel_hi:[1,1,0]
	v_pk_fma_f32 v[100:101], v[100:101], v[100:101], v[146:147]
	v_mul_f32_e32 v118, v36, v36
	v_pk_fma_f32 v[132:133], v[64:65], v[64:65], v[138:139] op_sel_hi:[1,1,0]
	v_pk_fma_f32 v[138:139], v[50:51], v[50:51], v[148:149] op_sel_hi:[1,1,0]
	v_pk_fma_f32 v[142:143], v[52:53], v[52:53], v[150:151] op_sel_hi:[1,1,0]
	v_mul_f32_e32 v106, v37, v37
	v_mov_b32_e32 v119, v103
	v_pk_add_f32 v[102:103], v[108:109], v[110:111]
	v_pk_add_f32 v[108:109], v[114:115], v[114:115] op_sel_hi:[0,1]
	v_pk_add_f32 v[104:105], v[104:105], v[112:113]
	v_pk_add_f32 v[110:111], v[122:123], v[122:123] op_sel_hi:[0,1]
	v_pk_add_f32 v[112:113], v[124:125], v[126:127]
	v_pk_add_f32 v[100:101], v[100:101], v[100:101] op_sel_hi:[0,1]
	v_pk_add_f32 v[114:115], v[134:135], v[136:137]
	v_mul_f32_e32 v128, v44, v44
	v_mul_f32_e32 v140, v32, v32
	v_mul_f32_e32 v152, v28, v28
	v_mul_f32_e32 v116, v48, v48
	v_mul_f32_e32 v120, v49, v49
	v_mul_f32_e32 v130, v34, v34
	v_mul_f32_e32 v132, v35, v35
	v_mul_f32_e32 v138, v30, v30
	v_mul_f32_e32 v142, v31, v31
	v_pk_add_f32 v[106:107], v[118:119], v[106:107]
	v_mul_f32_e32 v108, v45, v45
	v_mov_b32_e32 v129, v105
	v_mul_f32_e32 v110, v33, v33
	v_mov_b32_e32 v141, v113
	v_mul_f32_e32 v100, v29, v29
	v_mov_b32_e32 v153, v115
	v_pk_add_f32 v[104:105], v[116:117], v[120:121]
	v_pk_add_f32 v[112:113], v[130:131], v[132:133]
	v_pk_add_f32 v[114:115], v[138:139], v[142:143]
	v_pk_add_f32 v[102:103], v[106:107], v[102:103]
	v_pk_add_f32 v[106:107], v[128:129], v[108:109]
	v_pk_add_f32 v[108:109], v[140:141], v[110:111]
	v_pk_add_f32 v[100:101], v[152:153], v[100:101]
	v_add_f32_e32 v97, v102, v103
	v_pk_add_f32 v[102:103], v[106:107], v[104:105]
	v_pk_add_f32 v[104:105], v[108:109], v[112:113]
	v_pk_add_f32 v[100:101], v[100:101], v[114:115]
	v_add_f32_e32 v102, v102, v103
	v_add_f32_e32 v103, v104, v105
	v_add_f32_e32 v100, v100, v101
	ds_bpermute_b32 v101, v88, v97
	ds_bpermute_b32 v104, v88, v102
	ds_bpermute_b32 v105, v88, v103
	ds_bpermute_b32 v106, v88, v100
	s_waitcnt lgkmcnt(3)
	v_add_f32_e32 v97, v97, v101
	s_waitcnt lgkmcnt(2)
	v_add_f32_e32 v101, v102, v104
	s_waitcnt lgkmcnt(1)
	v_add_f32_e32 v102, v103, v105
	ds_bpermute_b32 v103, v89, v97
	s_waitcnt lgkmcnt(1)
	v_add_f32_e32 v100, v100, v106
	ds_bpermute_b32 v104, v89, v101
	ds_bpermute_b32 v105, v89, v102
	ds_bpermute_b32 v106, v89, v100
	s_waitcnt lgkmcnt(3)
	v_add_f32_e32 v97, v97, v103
	ds_bpermute_b32 v103, v90, v97
	s_waitcnt lgkmcnt(3)
	v_add_f32_e32 v101, v101, v104
	s_waitcnt lgkmcnt(2)
	v_add_f32_e32 v102, v102, v105
	s_waitcnt lgkmcnt(1)
	v_add_f32_e32 v100, v100, v106
	ds_bpermute_b32 v104, v90, v101
	ds_bpermute_b32 v105, v90, v102
	ds_bpermute_b32 v106, v90, v100
	s_waitcnt lgkmcnt(3)
	v_add_f32_e32 v97, v97, v103
	ds_bpermute_b32 v103, v91, v97
	s_waitcnt lgkmcnt(3)
	v_add_f32_e32 v101, v101, v104
	s_waitcnt lgkmcnt(2)
	v_add_f32_e32 v102, v102, v105
	s_waitcnt lgkmcnt(1)
	v_add_f32_e32 v100, v100, v106
	ds_bpermute_b32 v104, v91, v101
	ds_bpermute_b32 v105, v91, v102
	ds_bpermute_b32 v106, v91, v100
	s_waitcnt lgkmcnt(3)
	v_add_f32_e32 v97, v97, v103
	ds_bpermute_b32 v103, v92, v97
	s_waitcnt lgkmcnt(3)
	v_add_f32_e32 v101, v101, v104
	s_waitcnt lgkmcnt(2)
	v_add_f32_e32 v102, v102, v105
	s_waitcnt lgkmcnt(1)
	v_add_f32_e32 v100, v100, v106
	ds_bpermute_b32 v104, v92, v101
	ds_bpermute_b32 v105, v92, v102
	ds_bpermute_b32 v106, v92, v100
	s_waitcnt lgkmcnt(3)
	v_add_f32_e32 v97, v97, v103
	ds_bpermute_b32 v103, v93, v97
	s_waitcnt lgkmcnt(3)
	v_add_f32_e32 v101, v101, v104
	s_waitcnt lgkmcnt(2)
	v_add_f32_e32 v102, v102, v105
	s_waitcnt lgkmcnt(1)
	v_add_f32_e32 v100, v100, v106
	ds_bpermute_b32 v104, v93, v101
	ds_bpermute_b32 v105, v93, v102
	ds_bpermute_b32 v106, v93, v100
	s_waitcnt lgkmcnt(3)
	v_add_f32_e32 v97, v97, v103
	v_fmamk_f32 v97, v97, 0x3a800000, v95
	s_waitcnt lgkmcnt(2)
	v_add_f32_e32 v101, v101, v104
	v_mul_f32_e32 v103, 0x4f800000, v97
	v_cmp_gt_f32_e32 vcc, s16, v97
	s_waitcnt lgkmcnt(1)
	v_add_f32_e32 v102, v102, v105
	s_waitcnt lgkmcnt(0)
	v_add_f32_e32 v100, v100, v106
	v_fmamk_f32 v101, v101, 0x3a800000, v95
	v_cndmask_b32_e32 v97, v97, v103, vcc
	v_fmamk_f32 v102, v102, 0x3a800000, v95
	v_fmamk_f32 v100, v100, 0x3a800000, v95
	v_mul_f32_e32 v103, 0x4f800000, v101
	v_cmp_gt_f32_e64 s[2:3], s16, v101
	v_sqrt_f32_e32 v106, v97
	v_mul_f32_e32 v104, 0x4f800000, v102
	v_cmp_gt_f32_e64 s[4:5], s16, v102
	v_mul_f32_e32 v105, 0x4f800000, v100
	v_cmp_gt_f32_e64 s[6:7], s16, v100
	v_cndmask_b32_e64 v101, v101, v103, s[2:3]
	v_cndmask_b32_e64 v102, v102, v104, s[4:5]
	v_cndmask_b32_e64 v100, v100, v105, s[6:7]
	v_sqrt_f32_e32 v103, v101
	v_sqrt_f32_e32 v104, v102
	v_sqrt_f32_e32 v105, v100
	v_add_u32_e32 v107, -1, v106
	v_add_u32_e32 v108, 1, v106
	v_fma_f32 v109, -v107, v106, v97
	v_fma_f32 v110, -v108, v106, v97
	v_add_u32_e32 v111, -1, v103
	v_cmp_ge_f32_e64 s[8:9], 0, v109
	v_add_u32_e32 v112, 1, v103
	v_add_u32_e32 v113, -1, v104
	v_add_u32_e32 v115, -1, v105
	v_cndmask_b32_e64 v106, v106, v107, s[8:9]
	v_fma_f32 v107, -v111, v103, v101
	v_cmp_lt_f32_e64 s[8:9], 0, v110
	v_add_u32_e32 v114, 1, v104
	v_add_u32_e32 v116, 1, v105
	v_fma_f32 v109, -v112, v103, v101
	v_fma_f32 v117, -v113, v104, v102
	v_fma_f32 v119, -v115, v105, v100
	v_cndmask_b32_e64 v106, v106, v108, s[8:9]
	v_cmp_ge_f32_e64 s[8:9], 0, v107
	v_fma_f32 v118, -v114, v104, v102
	v_fma_f32 v120, -v116, v105, v100
	v_cndmask_b32_e64 v103, v103, v111, s[8:9]
	v_cmp_lt_f32_e64 s[8:9], 0, v109
	v_cmp_ge_f32_e64 s[10:11], 0, v117
	v_cmp_ge_f32_e64 s[12:13], 0, v119
	v_mul_f32_e32 v107, 0x37800000, v106
	v_cndmask_b32_e64 v104, v104, v113, s[10:11]
	v_cmp_lt_f32_e64 s[10:11], 0, v118
	v_cndmask_b32_e64 v105, v105, v115, s[12:13]
	v_cmp_lt_f32_e64 s[12:13], 0, v120
	v_cndmask_b32_e64 v103, v103, v112, s[8:9]
	v_cndmask_b32_e64 v104, v104, v114, s[10:11]
	v_cndmask_b32_e64 v105, v105, v116, s[12:13]
	v_cndmask_b32_e32 v106, v106, v107, vcc
	v_mul_f32_e32 v107, 0x37800000, v103
	v_cmp_class_f32_e32 vcc, v97, v96
	v_mul_f32_e32 v108, 0x37800000, v104
	v_mul_f32_e32 v109, 0x37800000, v105
	v_cndmask_b32_e32 v97, v106, v97, vcc
	v_cndmask_b32_e64 v103, v103, v107, s[2:3]
	v_cmp_class_f32_e32 vcc, v101, v96
	v_cndmask_b32_e64 v104, v104, v108, s[4:5]
	v_cmp_class_f32_e64 s[2:3], v102, v96
	v_cndmask_b32_e64 v105, v105, v109, s[6:7]
	v_cmp_class_f32_e64 s[4:5], v100, v96
	v_div_scale_f32 v106, s[6:7], v97, v97, 1.0
	v_cndmask_b32_e32 v108, v103, v101, vcc
	v_cndmask_b32_e64 v109, v104, v102, s[2:3]
	v_cndmask_b32_e64 v105, v105, v100, s[4:5]
	v_rcp_f32_e32 v100, v106
	v_div_scale_f32 v101, s[2:3], v108, v108, 1.0
	v_div_scale_f32 v103, s[4:5], v109, v109, 1.0
	v_rcp_f32_e32 v112, v101
	v_div_scale_f32 v110, s[8:9], v105, v105, 1.0
	v_rcp_f32_e32 v113, v103
	v_rcp_f32_e32 v114, v110
	v_fma_f32 v115, -v106, v100, 1.0
	v_div_scale_f32 v107, s[6:7], 1.0, v97, 1.0
	v_fmac_f32_e32 v100, v115, v100
	v_fma_f32 v115, -v101, v112, 1.0
	v_div_scale_f32 v102, s[2:3], 1.0, v108, 1.0
	v_fma_f32 v116, -v103, v113, 1.0
	v_mul_f32_e32 v118, v107, v100
	v_fmac_f32_e32 v112, v115, v112
	v_div_scale_f32 v104, s[4:5], 1.0, v109, 1.0
	v_fma_f32 v117, -v110, v114, 1.0
	v_fmac_f32_e32 v113, v116, v113
	v_fma_f32 v115, -v106, v118, v107
	v_mul_f32_e32 v116, v102, v112
	v_div_scale_f32 v111, s[8:9], 1.0, v105, 1.0
	v_fmac_f32_e32 v114, v117, v114
	v_mul_f32_e32 v117, v104, v113
	v_fmac_f32_e32 v118, v115, v100
	v_fma_f32 v115, -v101, v116, v102
	v_mul_f32_e32 v119, v111, v114
	v_fma_f32 v120, -v103, v117, v104
	v_fma_f32 v106, -v106, v118, v107
	v_fmac_f32_e32 v116, v115, v112
	s_mov_b64 vcc, s[6:7]
	v_fma_f32 v121, -v110, v119, v111
	v_fmac_f32_e32 v117, v120, v113
	v_div_fmas_f32 v100, v106, v100, v118
	v_fma_f32 v101, -v101, v116, v102
	s_mov_b64 vcc, s[2:3]
	v_fmac_f32_e32 v119, v121, v114
	v_fma_f32 v106, -v103, v117, v104
	v_div_fixup_f32 v100, v100, v97, 1.0
	v_div_fmas_f32 v97, v101, v112, v116
	s_mov_b64 vcc, s[4:5]
	v_fma_f32 v107, -v110, v119, v111
	v_pk_mul_f32 v[62:63], v[100:101], v[62:63] op_sel_hi:[0,1]
	v_pk_mul_f32 v[66:67], v[100:101], v[66:67] op_sel_hi:[0,1]
	v_pk_mul_f32 v[98:99], v[100:101], v[98:99] op_sel_hi:[0,1]
	v_pk_mul_f32 v[74:75], v[100:101], v[74:75] op_sel_hi:[0,1]
	v_pk_mul_f32 v[102:103], v[100:101], v[36:37] op_sel_hi:[0,1]
	v_div_fixup_f32 v104, v97, v108, 1.0
	v_div_fmas_f32 v97, v106, v113, v117
	s_mov_b64 vcc, s[8:9]
	v_pk_mul_f32 v[68:69], v[100:101], v[68:69] op_sel_hi:[0,1]
	v_pk_mul_f32 v[76:77], v[100:101], v[76:77] op_sel_hi:[0,1]
	v_pk_mul_f32 v[100:101], v[100:101], v[38:39] op_sel_hi:[0,1]
	v_pk_mul_f32 v[38:39], v[6:7], v[66:67]
	v_pk_mul_f32 v[36:37], v[4:5], v[62:63]
	v_pk_mul_f32 v[66:67], v[0:1], v[98:99]
	v_pk_mul_f32 v[74:75], v[12:13], v[74:75]
	v_pk_mul_f32 v[98:99], v[8:9], v[102:103]
	v_pk_mul_f32 v[62:63], v[104:105], v[70:71] op_sel_hi:[0,1]
	v_pk_mul_f32 v[70:71], v[104:105], v[72:73] op_sel_hi:[0,1]
	v_pk_mul_f32 v[44:45], v[104:105], v[44:45] op_sel_hi:[0,1]
	v_div_fixup_f32 v102, v97, v109, 1.0
	v_div_fmas_f32 v97, v107, v114, v119
	v_pk_mul_f32 v[68:69], v[2:3], v[68:69]
	v_pk_mul_f32 v[76:77], v[14:15], v[76:77]
	v_pk_mul_f32 v[100:101], v[10:11], v[100:101]
	v_pk_mul_f32 v[72:73], v[104:105], v[154:155] op_sel_hi:[0,1]
	v_pk_mul_f32 v[78:79], v[104:105], v[78:79] op_sel_hi:[0,1]
	v_pk_mul_f32 v[80:81], v[104:105], v[80:81] op_sel_hi:[0,1]
	v_pk_mul_f32 v[82:83], v[104:105], v[82:83] op_sel_hi:[0,1]
	v_pk_mul_f32 v[48:49], v[104:105], v[48:49] op_sel_hi:[0,1]
	global_store_dwordx4 v[26:27], v[36:39], off nt
	global_store_dwordx4 v[26:27], v[66:69], off offset:16 nt
	global_store_dwordx4 v[26:27], v[74:77], off offset:2048 nt
	global_store_dwordx4 v[26:27], v[98:101], off offset:2064 nt
	v_pk_mul_f32 v[38:39], v[6:7], v[70:71]
	v_pk_mul_f32 v[36:37], v[4:5], v[62:63]
	v_pk_mul_f32 v[74:75], v[8:9], v[44:45]
	v_pk_mul_f32 v[44:45], v[102:103], v[54:55] op_sel_hi:[0,1]
	v_pk_mul_f32 v[26:27], v[102:103], v[56:57] op_sel_hi:[0,1]
	v_pk_mul_f32 v[54:55], v[102:103], v[58:59] op_sel_hi:[0,1]
	v_pk_mul_f32 v[58:59], v[102:103], v[64:65] op_sel_hi:[0,1]
	v_div_fixup_f32 v64, v97, v105, 1.0
	v_pk_mul_f32 v[68:69], v[2:3], v[78:79]
	v_pk_mul_f32 v[66:67], v[0:1], v[72:73]
	v_pk_mul_f32 v[72:73], v[14:15], v[82:83]
	v_pk_mul_f32 v[70:71], v[12:13], v[80:81]
	v_pk_mul_f32 v[76:77], v[10:11], v[48:49]
	v_pk_mul_f32 v[48:49], v[102:103], v[86:87] op_sel_hi:[0,1]
	v_pk_mul_f32 v[56:57], v[102:103], v[60:61] op_sel_hi:[0,1]
	v_pk_mul_f32 v[60:61], v[102:103], v[32:33] op_sel_hi:[0,1]
	v_pk_mul_f32 v[62:63], v[102:103], v[34:35] op_sel_hi:[0,1]
	global_store_dwordx4 v[24:25], v[36:39], off nt
	global_store_dwordx4 v[24:25], v[66:69], off offset:16 nt
	global_store_dwordx4 v[24:25], v[70:73], off offset:2048 nt
	global_store_dwordx4 v[24:25], v[74:77], off offset:2064 nt
	v_pk_mul_f32 v[26:27], v[6:7], v[26:27]
	v_pk_mul_f32 v[24:25], v[4:5], v[44:45]
	v_pk_mul_f32 v[40:41], v[64:65], v[40:41] op_sel_hi:[0,1]
	v_pk_mul_f32 v[42:43], v[64:65], v[42:43] op_sel_hi:[0,1]
	v_pk_mul_f32 v[34:35], v[2:3], v[54:55]
	v_pk_mul_f32 v[32:33], v[0:1], v[48:49]
	v_pk_mul_f32 v[38:39], v[14:15], v[58:59]
	v_pk_mul_f32 v[36:37], v[12:13], v[56:57]
	v_pk_mul_f32 v[56:57], v[10:11], v[62:63]
	v_pk_mul_f32 v[54:55], v[8:9], v[60:61]
	v_pk_mul_f32 v[44:45], v[64:65], v[84:85] op_sel_hi:[0,1]
	v_pk_mul_f32 v[46:47], v[64:65], v[46:47] op_sel_hi:[0,1]
	v_pk_mul_f32 v[48:49], v[64:65], v[50:51] op_sel_hi:[0,1]
	v_pk_mul_f32 v[50:51], v[64:65], v[52:53] op_sel_hi:[0,1]
	v_pk_mul_f32 v[52:53], v[64:65], v[28:29] op_sel_hi:[0,1]
	v_pk_mul_f32 v[58:59], v[64:65], v[30:31] op_sel_hi:[0,1]
	global_store_dwordx4 v[22:23], v[24:27], off nt
	global_store_dwordx4 v[22:23], v[32:35], off offset:16 nt
	global_store_dwordx4 v[22:23], v[36:39], off offset:2048 nt
	global_store_dwordx4 v[22:23], v[54:57], off offset:2064 nt
	v_pk_mul_f32 v[24:25], v[6:7], v[42:43]
	v_pk_mul_f32 v[22:23], v[4:5], v[40:41]
	s_mov_b64 vcc, s[0:1]
	v_pk_mul_f32 v[28:29], v[2:3], v[46:47]
	v_pk_mul_f32 v[26:27], v[0:1], v[44:45]
	v_pk_mul_f32 v[32:33], v[14:15], v[50:51]
	v_pk_mul_f32 v[30:31], v[12:13], v[48:49]
	v_pk_mul_f32 v[36:37], v[10:11], v[58:59]
	v_pk_mul_f32 v[34:35], v[8:9], v[52:53]
	global_store_dwordx4 v[18:19], v[22:25], off nt
	global_store_dwordx4 v[18:19], v[26:29], off offset:16 nt
	global_store_dwordx4 v[18:19], v[30:33], off offset:2048 nt
	global_store_dwordx4 v[18:19], v[34:37], off offset:2064 nt
	s_cbranch_vccnz .LBB0_1054
